# recurrence waves start each block staggered by 64 cycles per wave index to de-phase their LDS bursts
# baseline (speedup 1.0000x reference)
; __device__ __forceinline__ void scan_half(const Params& p, LAS unsigned char* lds, int pi, int rh, int pass) {
;     ...
;         for (int it = 0; it < 66; ++it) {
;             if (it < 64) {
;                 const LAS float* rec = REC + (it & 1) * REC_BUF + 8 * j; const LAS float* vvp = VV + (it & 3) * 1024 + rowl; LAS float* yyp = YY + (it & 3) * 1024 + rowl;
;                 const LAS float* ssp = SSP + (it & 1) * 64 + 2 * (lane & 31);
;                 const float inv2 = __builtin_amdgcn_rcpf(fmaxf(ssp[0] + ssp[1], 1e-24f));
;                 f32x4 Rkk[2][2], Rw[2][2], Rka[2][2], Rkm[2][2], Rr[2][2]; float Rv[2];
;     ...
;                 LOADREC(0, 0);
;                 float yp = 0.f, yk0 = 0.f, yk1 = 0.f, yk2 = 0.f, yk3 = 0.f;
;     ...
; #pragma unroll
;                 for (int s = 0; s < 32; ++s) {
;                     const int c = s & 1, pc = c ^ 1;
;                     const float si = __int_as_float(__builtin_amdgcn_readlane(__float_as_int(inv2), s));
;                     f32x2 px, py, t01, t23, t45, t67; float x;
;                     f32x2 vv2; vv2.x = Rv[c]; asm volatile("" : "+v"(vv2));
;                     if (s >= 1) {
;                         VPKMUL(px, P01, Rkk[c][0].xy); VPKMUL(py, P01, Rr[pc][0].xy); VPKFMA(px, P23, Rkk[c][0].zw, px); VPKFMA(py, P23, Rr[pc][0].zw, py);
;                         VPKFMA(px, P45, Rkk[c][1].xy, px); VPKFMA(py, P45, Rr[pc][1].xy, py); VPKFMA(px, P67, Rkk[c][1].zw, px); VPKFMA(py, P67, Rr[pc][1].zw, py);
;                         VADD(x, px.x, px.y); VADD(yp, py.x, py.y);
;                     } else {
;                         VPKMUL(px, P01, Rkk[c][0].xy); VPKFMA(px, P23, Rkk[c][0].zw, px); VPKFMA(px, P45, Rkk[c][1].xy, px); VPKFMA(px, P67, Rkk[c][1].zw, px);
;                         VADD(x, px.x, px.y);
;                     }
;                     asm volatile("" ::: "memory");
;                     if (s + 1 < 32) LOADREC((s + 1) & 1, s + 1);
;                     asm volatile("" ::: "memory");
;                     VPKMULBL(t01, vv2, Rkm[c][0].xy); VPKMULBL(t23, vv2, Rkm[c][0].zw);
;                     VDPP1(x); if (s >= 1) VDPP1(yp);
;                     VPKMULBL(t45, vv2, Rkm[c][1].xy); VPKMULBL(t67, vv2, Rkm[c][1].zw);
;                     VDPP2(x); if (s >= 1) VDPP2(yp);
;                     VPKFMA(P01, P01, Rw[c][0].xy, t01); VPKFMA(P23, P23, Rw[c][0].zw, t23);
.Lscan_it:
	s_cmp_gt_u32 s9, 63
	s_cbranch_scc1 .Lscan_bar
	s_cmp_lt_u32 s80, 1
	s_cbranch_scc1 .Lstag_done
	s_sleep 1
	s_cmp_lt_u32 s80, 2
	s_cbranch_scc1 .Lstag_done
	s_sleep 1
	s_cmp_lt_u32 s80, 3
	s_cbranch_scc1 .Lstag_done
	s_sleep 1
.Lstag_done:
	s_and_b32 s10, s9, 1
	s_lshl_b32 s11, s10, 8
	v_add_u32_e32 v8, s11, v31
	ds_read_b64 v[8:9], v8
	s_mul_i32 s11, s10, 0xaa00
	s_and_b32 s10, s9, 3
	s_lshl_b32 s10, s10, 12
	v_add_u32_e32 v35, s11, v28
	v_add_u32_e32 v36, s10, v29
	v_add_u32_e32 v37, s10, v30
	v_add_u32_e32 v38, s10, v26
	ds_read_b128 v[48:51], v35 offset:0
	ds_read_b128 v[60:63], v35 offset:26112
	ds_read_b32 v92, v36 offset:0
	ds_read_b32 v93, v38 offset:0
	ds_read_b128 v[52:55], v35 offset:8704
	ds_read_b128 v[56:59], v35 offset:17408
	ds_read_b128 v[80:83], v35 offset:34816
	s_waitcnt lgkmcnt(7)
	v_add_f32_e32 v8, v8, v9
	v_max_f32_e32 v8, 0x179abe15, v8
	v_rcp_f32_e32 v34, v8
	s_waitcnt lgkmcnt(0)
	ds_read_b128 v[64:67], v35 offset:272
	ds_read_b128 v[76:79], v35 offset:26384
	ds_read_b32 v94, v36 offset:128
	ds_read_b32 v95, v38 offset:128
	ds_read_b128 v[68:71], v35 offset:8976
	ds_read_b128 v[72:75], v35 offset:17680
	ds_read_b128 v[84:87], v35 offset:35088
	v_pk_mul_f32 v[8:9], v[0:1], v[48:49] op_sel_hi:[1,0]
	v_pk_fma_f32 v[8:9], v[2:3], v[48:49], v[8:9] op_sel:[0,1,0] op_sel_hi:[1,1,1]
	v_pk_fma_f32 v[8:9], v[4:5], v[50:51], v[8:9] op_sel_hi:[1,0,1]
	v_pk_fma_f32 v[8:9], v[6:7], v[50:51], v[8:9] op_sel:[0,1,0] op_sel_hi:[1,1,1]
	v_readlane_b32 s10, v34, 0
	v_pk_mul_f32 v[16:17], v[92:93], v[60:61] op_sel_hi:[1,0]
	v_pk_mul_f32 v[18:19], v[92:93], v[60:61] op_sel:[0,1] op_sel_hi:[1,1]
	v_add_f32_dpp v8, v9, v8 quad_perm:[1,0,3,2] row_mask:0xf bank_mask:0xf bound_ctrl:1
	v_pk_mul_f32 v[20:21], v[92:93], v[62:63] op_sel_hi:[1,0]
	v_pk_mul_f32 v[22:23], v[92:93], v[62:63] op_sel:[0,1] op_sel_hi:[1,1]
	v_add_f32_dpp v8, v8, v8 quad_perm:[2,3,0,1] row_mask:0xf bank_mask:0xf bound_ctrl:1
	v_pk_fma_f32 v[0:1], v[0:1], v[52:53], v[16:17] op_sel_hi:[1,0,1]
	v_pk_fma_f32 v[2:3], v[2:3], v[52:53], v[18:19] op_sel:[0,1,0] op_sel_hi:[1,1,1]
	v_add_f32_dpp v8, v8, v8 row_ror:4 row_mask:0xf bank_mask:0xf bound_ctrl:1
	v_pk_fma_f32 v[4:5], v[4:5], v[54:55], v[20:21] op_sel_hi:[1,0,1]
	s_nop 0
	v_add_f32_dpp v8, v8, v8 row_ror:8 row_mask:0xf bank_mask:0xf bound_ctrl:1
	v_mul_f32_e32 v8, s10, v8
	v_pk_fma_f32 v[6:7], v[6:7], v[54:55], v[22:23] op_sel:[0,1,0] op_sel_hi:[1,1,1]
	s_nop 0
	v_mov_b32_dpp v9, v8 quad_perm:[1,0,3,2] row_mask:0xf bank_mask:0xf
	v_pk_fma_f32 v[0:1], v[8:9], v[56:57], v[0:1] op_sel_hi:[1,0,1] neg_lo:[1,0,0] neg_hi:[1,0,0]
	v_pk_fma_f32 v[2:3], v[8:9], v[56:57], v[2:3] op_sel:[0,1,0] op_sel_hi:[1,1,1] neg_lo:[1,0,0] neg_hi:[1,0,0]
	v_pk_fma_f32 v[4:5], v[8:9], v[58:59], v[4:5] op_sel_hi:[1,0,1] neg_lo:[1,0,0] neg_hi:[1,0,0]
	v_pk_fma_f32 v[6:7], v[8:9], v[58:59], v[6:7] op_sel:[0,1,0] op_sel_hi:[1,1,1] neg_lo:[1,0,0] neg_hi:[1,0,0]
	s_waitcnt lgkmcnt(0)
	ds_read_b128 v[48:51], v35 offset:544
	ds_read_b128 v[60:63], v35 offset:26656
	ds_read_b32 v92, v36 offset:256
	ds_read_b32 v93, v38 offset:256
	ds_read_b128 v[52:55], v35 offset:9248
	ds_read_b128 v[56:59], v35 offset:17952
	ds_read_b128 v[88:91], v35 offset:35360
	v_pk_mul_f32 v[8:9], v[0:1], v[64:65] op_sel_hi:[1,0]
	v_pk_mul_f32 v[10:11], v[0:1], v[80:81] op_sel_hi:[1,0]
	v_pk_fma_f32 v[8:9], v[2:3], v[64:65], v[8:9] op_sel:[0,1,0] op_sel_hi:[1,1,1]
	v_pk_fma_f32 v[10:11], v[2:3], v[80:81], v[10:11] op_sel:[0,1,0] op_sel_hi:[1,1,1]
	v_pk_fma_f32 v[8:9], v[4:5], v[66:67], v[8:9] op_sel_hi:[1,0,1]
	v_pk_fma_f32 v[10:11], v[4:5], v[82:83], v[10:11] op_sel_hi:[1,0,1]
	v_pk_fma_f32 v[8:9], v[6:7], v[66:67], v[8:9] op_sel:[0,1,0] op_sel_hi:[1,1,1]
	v_pk_fma_f32 v[10:11], v[6:7], v[82:83], v[10:11] op_sel:[0,1,0] op_sel_hi:[1,1,1]
	v_readlane_b32 s10, v34, 1
	v_pk_mul_f32 v[16:17], v[94:95], v[76:77] op_sel_hi:[1,0]
	v_pk_mul_f32 v[18:19], v[94:95], v[76:77] op_sel:[0,1] op_sel_hi:[1,1]
	v_add_f32_dpp v8, v9, v8 quad_perm:[1,0,3,2] row_mask:0xf bank_mask:0xf bound_ctrl:1
	v_add_f32_dpp v10, v11, v10 quad_perm:[1,0,3,2] row_mask:0xf bank_mask:0xf bound_ctrl:1
	v_pk_mul_f32 v[20:21], v[94:95], v[78:79] op_sel_hi:[1,0]
	v_pk_mul_f32 v[22:23], v[94:95], v[78:79] op_sel:[0,1] op_sel_hi:[1,1]
	v_add_f32_dpp v8, v8, v8 quad_perm:[2,3,0,1] row_mask:0xf bank_mask:0xf bound_ctrl:1
	v_add_f32_dpp v10, v10, v10 quad_perm:[2,3,0,1] row_mask:0xf bank_mask:0xf bound_ctrl:1
	v_pk_fma_f32 v[0:1], v[0:1], v[68:69], v[16:17] op_sel_hi:[1,0,1]
	v_pk_fma_f32 v[2:3], v[2:3], v[68:69], v[18:19] op_sel:[0,1,0] op_sel_hi:[1,1,1]
	v_add_f32_dpp v8, v8, v8 row_ror:4 row_mask:0xf bank_mask:0xf bound_ctrl:1
	v_add_f32_dpp v10, v10, v10 row_ror:4 row_mask:0xf bank_mask:0xf bound_ctrl:1
	v_pk_fma_f32 v[4:5], v[4:5], v[70:71], v[20:21] op_sel_hi:[1,0,1]
	v_add_f32_dpp v8, v8, v8 row_ror:8 row_mask:0xf bank_mask:0xf bound_ctrl:1
	v_mul_f32_e32 v8, s10, v8
	v_add_f32_dpp v96, v10, v10 row_ror:8 row_mask:0xf bank_mask:0x1 bound_ctrl:1
	v_pk_fma_f32 v[6:7], v[6:7], v[70:71], v[22:23] op_sel:[0,1,0] op_sel_hi:[1,1,1]
	v_mov_b32_dpp v9, v8 quad_perm:[1,0,3,2] row_mask:0xf bank_mask:0xf
	v_pk_fma_f32 v[0:1], v[8:9], v[72:73], v[0:1] op_sel_hi:[1,0,1] neg_lo:[1,0,0] neg_hi:[1,0,0]
	v_pk_fma_f32 v[2:3], v[8:9], v[72:73], v[2:3] op_sel:[0,1,0] op_sel_hi:[1,1,1] neg_lo:[1,0,0] neg_hi:[1,0,0]
	v_pk_fma_f32 v[4:5], v[8:9], v[74:75], v[4:5] op_sel_hi:[1,0,1] neg_lo:[1,0,0] neg_hi:[1,0,0]
	v_pk_fma_f32 v[6:7], v[8:9], v[74:75], v[6:7] op_sel:[0,1,0] op_sel_hi:[1,1,1] neg_lo:[1,0,0] neg_hi:[1,0,0]
	s_waitcnt lgkmcnt(0)
; #define VPKMUL(d, a, b) asm volatile("v_pk_mul_f32 %0, %1, %2" : "=v"(d) : "v"(a), "v"(b))
; __device__ __forceinline__ void scan_half(const Params& p, LAS unsigned char* lds, int pi, int rh, int pass) {
;     ...
;                 LOADREC(0, 0);
;                 float yp = 0.f, yk0 = 0.f, yk1 = 0.f, yk2 = 0.f, yk3 = 0.f;
;     ...
; #pragma unroll
;                 for (int s = 0; s < 32; ++s) {
;                     const int c = s & 1, pc = c ^ 1;
;                     const float si = __int_as_float(__builtin_amdgcn_readlane(__float_as_int(inv2), s));
;                     f32x2 px, py, t01, t23, t45, t67; float x;
;                     f32x2 vv2; vv2.x = Rv[c]; asm volatile("" : "+v"(vv2));
;                     if (s >= 1) {
;                         VPKMUL(px, P01, Rkk[c][0].xy); VPKMUL(py, P01, Rr[pc][0].xy); VPKFMA(px, P23, Rkk[c][0].zw, px); VPKFMA(py, P23, Rr[pc][0].zw, py);
;                         VPKFMA(px, P45, Rkk[c][1].xy, px); VPKFMA(py, P45, Rr[pc][1].xy, py); VPKFMA(px, P67, Rkk[c][1].zw, px); VPKFMA(py, P67, Rr[pc][1].zw, py);
;                         VADD(x, px.x, px.y); VADD(yp, py.x, py.y);
;                     } else {
;                         VPKMUL(px, P01, Rkk[c][0].xy); VPKFMA(px, P23, Rkk[c][0].zw, px); VPKFMA(px, P45, Rkk[c][1].xy, px); VPKFMA(px, P67, Rkk[c][1].zw, px);
;                         VADD(x, px.x, px.y);
;                     }
;                     asm volatile("" ::: "memory");
;                     if (s + 1 < 32) LOADREC((s + 1) & 1, s + 1);
;                     asm volatile("" ::: "memory");
;                     VPKMULBL(t01, vv2, Rkm[c][0].xy); VPKMULBL(t23, vv2, Rkm[c][0].zw);
;                     VDPP1(x); if (s >= 1) VDPP1(yp);
;                     VPKMULBL(t45, vv2, Rkm[c][1].xy); VPKMULBL(t67, vv2, Rkm[c][1].zw);
;                     VDPP2(x); if (s >= 1) VDPP2(yp);
;                     VPKFMA(P01, P01, Rw[c][0].xy, t01); VPKFMA(P23, P23, Rw[c][0].zw, t23);
;                     VDPP3(x); if (s >= 1) VDPP3(yp);
;                     VPKFMA(P45, P45, Rw[c][1].xy, t45); VPKFMA(P67, P67, Rw[c][1].zw, t67);
;                     if (s >= 1) { if (s - 1 < 8) YSHIFT(yk0); else if (s - 1 < 16) YSHIFT(yk1); else if (s - 1 < 24) YSHIFT(yk2); else YSHIFT(yk3); }
;                     x = x * si;
;                     f32x2 x2; x2.x = x; asm volatile("" : "+v"(x2));
	ds_read_b128 v[64:67], v35 offset:816
	ds_read_b128 v[76:79], v35 offset:26928
	ds_read_b32 v94, v36 offset:384
	ds_read_b32 v95, v38 offset:384
	ds_read_b128 v[68:71], v35 offset:9520
	ds_read_b128 v[72:75], v35 offset:18224
	ds_read_b128 v[80:83], v35 offset:35632
	v_pk_mul_f32 v[8:9], v[0:1], v[48:49] op_sel_hi:[1,0]
	v_pk_mul_f32 v[10:11], v[0:1], v[84:85] op_sel_hi:[1,0]
	v_pk_fma_f32 v[8:9], v[2:3], v[48:49], v[8:9] op_sel:[0,1,0] op_sel_hi:[1,1,1]
	v_pk_fma_f32 v[10:11], v[2:3], v[84:85], v[10:11] op_sel:[0,1,0] op_sel_hi:[1,1,1]
	v_pk_fma_f32 v[8:9], v[4:5], v[50:51], v[8:9] op_sel_hi:[1,0,1]
	v_pk_fma_f32 v[10:11], v[4:5], v[86:87], v[10:11] op_sel_hi:[1,0,1]
	v_pk_fma_f32 v[8:9], v[6:7], v[50:51], v[8:9] op_sel:[0,1,0] op_sel_hi:[1,1,1]
	v_pk_fma_f32 v[10:11], v[6:7], v[86:87], v[10:11] op_sel:[0,1,0] op_sel_hi:[1,1,1]
	v_readlane_b32 s10, v34, 2
	v_pk_mul_f32 v[16:17], v[92:93], v[60:61] op_sel_hi:[1,0]
	v_pk_mul_f32 v[18:19], v[92:93], v[60:61] op_sel:[0,1] op_sel_hi:[1,1]
	v_add_f32_dpp v8, v9, v8 quad_perm:[1,0,3,2] row_mask:0xf bank_mask:0xf bound_ctrl:1
	v_add_f32_dpp v10, v11, v10 quad_perm:[1,0,3,2] row_mask:0xf bank_mask:0xf bound_ctrl:1
	v_pk_mul_f32 v[20:21], v[92:93], v[62:63] op_sel_hi:[1,0]
	v_pk_mul_f32 v[22:23], v[92:93], v[62:63] op_sel:[0,1] op_sel_hi:[1,1]
	v_add_f32_dpp v8, v8, v8 quad_perm:[2,3,0,1] row_mask:0xf bank_mask:0xf bound_ctrl:1
	v_add_f32_dpp v10, v10, v10 quad_perm:[2,3,0,1] row_mask:0xf bank_mask:0xf bound_ctrl:1
	v_pk_fma_f32 v[0:1], v[0:1], v[52:53], v[16:17] op_sel_hi:[1,0,1]
	v_pk_fma_f32 v[2:3], v[2:3], v[52:53], v[18:19] op_sel:[0,1,0] op_sel_hi:[1,1,1]
	v_add_f32_dpp v8, v8, v8 row_ror:4 row_mask:0xf bank_mask:0xf bound_ctrl:1
	v_add_f32_dpp v10, v10, v10 row_ror:4 row_mask:0xf bank_mask:0xf bound_ctrl:1
	v_pk_fma_f32 v[4:5], v[4:5], v[54:55], v[20:21] op_sel_hi:[1,0,1]
	v_add_f32_dpp v8, v8, v8 row_ror:8 row_mask:0xf bank_mask:0xf bound_ctrl:1
	v_mul_f32_e32 v8, s10, v8
	v_add_f32_dpp v96, v10, v10 row_ror:8 row_mask:0xf bank_mask:0x2 bound_ctrl:1
	v_pk_fma_f32 v[6:7], v[6:7], v[54:55], v[22:23] op_sel:[0,1,0] op_sel_hi:[1,1,1]
	v_mov_b32_dpp v9, v8 quad_perm:[1,0,3,2] row_mask:0xf bank_mask:0xf
	v_pk_fma_f32 v[0:1], v[8:9], v[56:57], v[0:1] op_sel_hi:[1,0,1] neg_lo:[1,0,0] neg_hi:[1,0,0]
	v_pk_fma_f32 v[2:3], v[8:9], v[56:57], v[2:3] op_sel:[0,1,0] op_sel_hi:[1,1,1] neg_lo:[1,0,0] neg_hi:[1,0,0]
	v_pk_fma_f32 v[4:5], v[8:9], v[58:59], v[4:5] op_sel_hi:[1,0,1] neg_lo:[1,0,0] neg_hi:[1,0,0]
	v_pk_fma_f32 v[6:7], v[8:9], v[58:59], v[6:7] op_sel:[0,1,0] op_sel_hi:[1,1,1] neg_lo:[1,0,0] neg_hi:[1,0,0]
	s_waitcnt lgkmcnt(0)
	ds_read_b128 v[48:51], v35 offset:1088
	ds_read_b128 v[60:63], v35 offset:27200
	ds_read_b32 v92, v36 offset:512
	ds_read_b32 v93, v38 offset:512
	ds_read_b128 v[52:55], v35 offset:9792
	ds_read_b128 v[56:59], v35 offset:18496
	ds_read_b128 v[84:87], v35 offset:35904
	v_pk_mul_f32 v[8:9], v[0:1], v[64:65] op_sel_hi:[1,0]
	v_pk_mul_f32 v[10:11], v[0:1], v[88:89] op_sel_hi:[1,0]
	v_pk_fma_f32 v[8:9], v[2:3], v[64:65], v[8:9] op_sel:[0,1,0] op_sel_hi:[1,1,1]
	v_pk_fma_f32 v[10:11], v[2:3], v[88:89], v[10:11] op_sel:[0,1,0] op_sel_hi:[1,1,1]
	v_pk_fma_f32 v[8:9], v[4:5], v[66:67], v[8:9] op_sel_hi:[1,0,1]
	v_pk_fma_f32 v[10:11], v[4:5], v[90:91], v[10:11] op_sel_hi:[1,0,1]
	v_pk_fma_f32 v[8:9], v[6:7], v[66:67], v[8:9] op_sel:[0,1,0] op_sel_hi:[1,1,1]
	v_pk_fma_f32 v[10:11], v[6:7], v[90:91], v[10:11] op_sel:[0,1,0] op_sel_hi:[1,1,1]
	v_readlane_b32 s10, v34, 3
	v_pk_mul_f32 v[16:17], v[94:95], v[76:77] op_sel_hi:[1,0]
	v_pk_mul_f32 v[18:19], v[94:95], v[76:77] op_sel:[0,1] op_sel_hi:[1,1]
	v_add_f32_dpp v8, v9, v8 quad_perm:[1,0,3,2] row_mask:0xf bank_mask:0xf bound_ctrl:1
	v_add_f32_dpp v10, v11, v10 quad_perm:[1,0,3,2] row_mask:0xf bank_mask:0xf bound_ctrl:1
	v_pk_mul_f32 v[20:21], v[94:95], v[78:79] op_sel_hi:[1,0]
	v_pk_mul_f32 v[22:23], v[94:95], v[78:79] op_sel:[0,1] op_sel_hi:[1,1]
	v_add_f32_dpp v8, v8, v8 quad_perm:[2,3,0,1] row_mask:0xf bank_mask:0xf bound_ctrl:1
	v_add_f32_dpp v10, v10, v10 quad_perm:[2,3,0,1] row_mask:0xf bank_mask:0xf bound_ctrl:1
	v_pk_fma_f32 v[0:1], v[0:1], v[68:69], v[16:17] op_sel_hi:[1,0,1]
	v_pk_fma_f32 v[2:3], v[2:3], v[68:69], v[18:19] op_sel:[0,1,0] op_sel_hi:[1,1,1]
	v_add_f32_dpp v8, v8, v8 row_ror:4 row_mask:0xf bank_mask:0xf bound_ctrl:1
	v_add_f32_dpp v10, v10, v10 row_ror:4 row_mask:0xf bank_mask:0xf bound_ctrl:1
	v_pk_fma_f32 v[4:5], v[4:5], v[70:71], v[20:21] op_sel_hi:[1,0,1]
	v_add_f32_dpp v8, v8, v8 row_ror:8 row_mask:0xf bank_mask:0xf bound_ctrl:1
	v_mul_f32_e32 v8, s10, v8
	v_add_f32_dpp v96, v10, v10 row_ror:8 row_mask:0xf bank_mask:0x4 bound_ctrl:1
	v_pk_fma_f32 v[6:7], v[6:7], v[70:71], v[22:23] op_sel:[0,1,0] op_sel_hi:[1,1,1]
	v_mov_b32_dpp v9, v8 quad_perm:[1,0,3,2] row_mask:0xf bank_mask:0xf
	v_pk_fma_f32 v[0:1], v[8:9], v[72:73], v[0:1] op_sel_hi:[1,0,1] neg_lo:[1,0,0] neg_hi:[1,0,0]
	v_pk_fma_f32 v[2:3], v[8:9], v[72:73], v[2:3] op_sel:[0,1,0] op_sel_hi:[1,1,1] neg_lo:[1,0,0] neg_hi:[1,0,0]
	v_pk_fma_f32 v[4:5], v[8:9], v[74:75], v[4:5] op_sel_hi:[1,0,1] neg_lo:[1,0,0] neg_hi:[1,0,0]
	v_pk_fma_f32 v[6:7], v[8:9], v[74:75], v[6:7] op_sel:[0,1,0] op_sel_hi:[1,1,1] neg_lo:[1,0,0] neg_hi:[1,0,0]
	s_waitcnt lgkmcnt(0)
; #define VPKMUL(d, a, b) asm volatile("v_pk_mul_f32 %0, %1, %2" : "=v"(d) : "v"(a), "v"(b))
; __device__ __forceinline__ void scan_half(const Params& p, LAS unsigned char* lds, int pi, int rh, int pass) {
;     ...
;                 LOADREC(0, 0);
;                 float yp = 0.f, yk0 = 0.f, yk1 = 0.f, yk2 = 0.f, yk3 = 0.f;
;     ...
; #pragma unroll
;                 for (int s = 0; s < 32; ++s) {
;                     const int c = s & 1, pc = c ^ 1;
;                     const float si = __int_as_float(__builtin_amdgcn_readlane(__float_as_int(inv2), s));
;                     f32x2 px, py, t01, t23, t45, t67; float x;
;                     f32x2 vv2; vv2.x = Rv[c]; asm volatile("" : "+v"(vv2));
;                     if (s >= 1) {
;                         VPKMUL(px, P01, Rkk[c][0].xy); VPKMUL(py, P01, Rr[pc][0].xy); VPKFMA(px, P23, Rkk[c][0].zw, px); VPKFMA(py, P23, Rr[pc][0].zw, py);
;                         VPKFMA(px, P45, Rkk[c][1].xy, px); VPKFMA(py, P45, Rr[pc][1].xy, py); VPKFMA(px, P67, Rkk[c][1].zw, px); VPKFMA(py, P67, Rr[pc][1].zw, py);
;                         VADD(x, px.x, px.y); VADD(yp, py.x, py.y);
;                     } else {
;                         VPKMUL(px, P01, Rkk[c][0].xy); VPKFMA(px, P23, Rkk[c][0].zw, px); VPKFMA(px, P45, Rkk[c][1].xy, px); VPKFMA(px, P67, Rkk[c][1].zw, px);
;                         VADD(x, px.x, px.y);
;                     }
;                     asm volatile("" ::: "memory");
;                     if (s + 1 < 32) LOADREC((s + 1) & 1, s + 1);
;                     asm volatile("" ::: "memory");
;                     VPKMULBL(t01, vv2, Rkm[c][0].xy); VPKMULBL(t23, vv2, Rkm[c][0].zw);
;                     VDPP1(x); if (s >= 1) VDPP1(yp);
;                     VPKMULBL(t45, vv2, Rkm[c][1].xy); VPKMULBL(t67, vv2, Rkm[c][1].zw);
;                     VDPP2(x); if (s >= 1) VDPP2(yp);
;                     VPKFMA(P01, P01, Rw[c][0].xy, t01); VPKFMA(P23, P23, Rw[c][0].zw, t23);
;                     VDPP3(x); if (s >= 1) VDPP3(yp);
;                     VPKFMA(P45, P45, Rw[c][1].xy, t45); VPKFMA(P67, P67, Rw[c][1].zw, t67);
;                     if (s >= 1) { if (s - 1 < 8) YSHIFT(yk0); else if (s - 1 < 16) YSHIFT(yk1); else if (s - 1 < 24) YSHIFT(yk2); else YSHIFT(yk3); }
;                     x = x * si;
;                     f32x2 x2; x2.x = x; asm volatile("" : "+v"(x2));
	ds_read_b128 v[64:67], v35 offset:1360
	ds_read_b128 v[76:79], v35 offset:27472
	ds_read_b32 v94, v36 offset:640
	ds_read_b32 v95, v38 offset:640
	ds_read_b128 v[68:71], v35 offset:10064
	ds_read_b128 v[72:75], v35 offset:18768
	ds_read_b128 v[88:91], v35 offset:36176
	v_pk_mul_f32 v[8:9], v[0:1], v[48:49] op_sel_hi:[1,0]
	v_pk_mul_f32 v[10:11], v[0:1], v[80:81] op_sel_hi:[1,0]
	v_pk_fma_f32 v[8:9], v[2:3], v[48:49], v[8:9] op_sel:[0,1,0] op_sel_hi:[1,1,1]
	v_pk_fma_f32 v[10:11], v[2:3], v[80:81], v[10:11] op_sel:[0,1,0] op_sel_hi:[1,1,1]
	v_pk_fma_f32 v[8:9], v[4:5], v[50:51], v[8:9] op_sel_hi:[1,0,1]
	v_pk_fma_f32 v[10:11], v[4:5], v[82:83], v[10:11] op_sel_hi:[1,0,1]
	v_pk_fma_f32 v[8:9], v[6:7], v[50:51], v[8:9] op_sel:[0,1,0] op_sel_hi:[1,1,1]
	v_pk_fma_f32 v[10:11], v[6:7], v[82:83], v[10:11] op_sel:[0,1,0] op_sel_hi:[1,1,1]
	v_readlane_b32 s10, v34, 4
	v_pk_mul_f32 v[16:17], v[92:93], v[60:61] op_sel_hi:[1,0]
	v_pk_mul_f32 v[18:19], v[92:93], v[60:61] op_sel:[0,1] op_sel_hi:[1,1]
	v_add_f32_dpp v8, v9, v8 quad_perm:[1,0,3,2] row_mask:0xf bank_mask:0xf bound_ctrl:1
	v_add_f32_dpp v10, v11, v10 quad_perm:[1,0,3,2] row_mask:0xf bank_mask:0xf bound_ctrl:1
	v_pk_mul_f32 v[20:21], v[92:93], v[62:63] op_sel_hi:[1,0]
	v_pk_mul_f32 v[22:23], v[92:93], v[62:63] op_sel:[0,1] op_sel_hi:[1,1]
	v_add_f32_dpp v8, v8, v8 quad_perm:[2,3,0,1] row_mask:0xf bank_mask:0xf bound_ctrl:1
	v_add_f32_dpp v10, v10, v10 quad_perm:[2,3,0,1] row_mask:0xf bank_mask:0xf bound_ctrl:1
	v_pk_fma_f32 v[0:1], v[0:1], v[52:53], v[16:17] op_sel_hi:[1,0,1]
	v_pk_fma_f32 v[2:3], v[2:3], v[52:53], v[18:19] op_sel:[0,1,0] op_sel_hi:[1,1,1]
	v_add_f32_dpp v8, v8, v8 row_ror:4 row_mask:0xf bank_mask:0xf bound_ctrl:1
	v_add_f32_dpp v10, v10, v10 row_ror:4 row_mask:0xf bank_mask:0xf bound_ctrl:1
	v_pk_fma_f32 v[4:5], v[4:5], v[54:55], v[20:21] op_sel_hi:[1,0,1]
	v_add_f32_dpp v8, v8, v8 row_ror:8 row_mask:0xf bank_mask:0xf bound_ctrl:1
	v_mul_f32_e32 v8, s10, v8
	v_add_f32_dpp v96, v10, v10 row_ror:8 row_mask:0xf bank_mask:0x8 bound_ctrl:1
	v_pk_fma_f32 v[6:7], v[6:7], v[54:55], v[22:23] op_sel:[0,1,0] op_sel_hi:[1,1,1]
	v_mov_b32_dpp v9, v8 quad_perm:[1,0,3,2] row_mask:0xf bank_mask:0xf
	v_pk_fma_f32 v[0:1], v[8:9], v[56:57], v[0:1] op_sel_hi:[1,0,1] neg_lo:[1,0,0] neg_hi:[1,0,0]
	v_pk_fma_f32 v[2:3], v[8:9], v[56:57], v[2:3] op_sel:[0,1,0] op_sel_hi:[1,1,1] neg_lo:[1,0,0] neg_hi:[1,0,0]
	v_pk_fma_f32 v[4:5], v[8:9], v[58:59], v[4:5] op_sel_hi:[1,0,1] neg_lo:[1,0,0] neg_hi:[1,0,0]
	v_pk_fma_f32 v[6:7], v[8:9], v[58:59], v[6:7] op_sel:[0,1,0] op_sel_hi:[1,1,1] neg_lo:[1,0,0] neg_hi:[1,0,0]
	s_waitcnt lgkmcnt(0)
	ds_read_b128 v[48:51], v35 offset:1632
	ds_read_b128 v[60:63], v35 offset:27744
	ds_read_b32 v92, v36 offset:768
	ds_read_b32 v93, v38 offset:768
	ds_read_b128 v[52:55], v35 offset:10336
	ds_read_b128 v[56:59], v35 offset:19040
	ds_read_b128 v[80:83], v35 offset:36448
	v_pk_mul_f32 v[8:9], v[0:1], v[64:65] op_sel_hi:[1,0]
	v_pk_mul_f32 v[10:11], v[0:1], v[84:85] op_sel_hi:[1,0]
	v_pk_fma_f32 v[8:9], v[2:3], v[64:65], v[8:9] op_sel:[0,1,0] op_sel_hi:[1,1,1]
	v_pk_fma_f32 v[10:11], v[2:3], v[84:85], v[10:11] op_sel:[0,1,0] op_sel_hi:[1,1,1]
	v_pk_fma_f32 v[8:9], v[4:5], v[66:67], v[8:9] op_sel_hi:[1,0,1]
	v_pk_fma_f32 v[10:11], v[4:5], v[86:87], v[10:11] op_sel_hi:[1,0,1]
	v_pk_fma_f32 v[8:9], v[6:7], v[66:67], v[8:9] op_sel:[0,1,0] op_sel_hi:[1,1,1]
	v_pk_fma_f32 v[10:11], v[6:7], v[86:87], v[10:11] op_sel:[0,1,0] op_sel_hi:[1,1,1]
	v_readlane_b32 s10, v34, 5
	v_pk_mul_f32 v[16:17], v[94:95], v[76:77] op_sel_hi:[1,0]
	v_pk_mul_f32 v[18:19], v[94:95], v[76:77] op_sel:[0,1] op_sel_hi:[1,1]
	v_add_f32_dpp v8, v9, v8 quad_perm:[1,0,3,2] row_mask:0xf bank_mask:0xf bound_ctrl:1
	v_add_f32_dpp v10, v11, v10 quad_perm:[1,0,3,2] row_mask:0xf bank_mask:0xf bound_ctrl:1
	v_pk_mul_f32 v[20:21], v[94:95], v[78:79] op_sel_hi:[1,0]
	v_pk_mul_f32 v[22:23], v[94:95], v[78:79] op_sel:[0,1] op_sel_hi:[1,1]
	v_add_f32_dpp v8, v8, v8 quad_perm:[2,3,0,1] row_mask:0xf bank_mask:0xf bound_ctrl:1
	v_add_f32_dpp v10, v10, v10 quad_perm:[2,3,0,1] row_mask:0xf bank_mask:0xf bound_ctrl:1
	v_pk_fma_f32 v[0:1], v[0:1], v[68:69], v[16:17] op_sel_hi:[1,0,1]
	v_pk_fma_f32 v[2:3], v[2:3], v[68:69], v[18:19] op_sel:[0,1,0] op_sel_hi:[1,1,1]
	v_add_f32_dpp v8, v8, v8 row_ror:4 row_mask:0xf bank_mask:0xf bound_ctrl:1
	v_add_f32_dpp v10, v10, v10 row_ror:4 row_mask:0xf bank_mask:0xf bound_ctrl:1
	v_pk_fma_f32 v[4:5], v[4:5], v[70:71], v[20:21] op_sel_hi:[1,0,1]
	v_add_f32_dpp v8, v8, v8 row_ror:8 row_mask:0xf bank_mask:0xf bound_ctrl:1
	v_mul_f32_e32 v8, s10, v8
	v_add_f32_dpp v97, v10, v10 row_ror:8 row_mask:0xf bank_mask:0x1 bound_ctrl:1
	v_pk_fma_f32 v[6:7], v[6:7], v[70:71], v[22:23] op_sel:[0,1,0] op_sel_hi:[1,1,1]
	v_mov_b32_dpp v9, v8 quad_perm:[1,0,3,2] row_mask:0xf bank_mask:0xf
	v_pk_fma_f32 v[0:1], v[8:9], v[72:73], v[0:1] op_sel_hi:[1,0,1] neg_lo:[1,0,0] neg_hi:[1,0,0]
	v_pk_fma_f32 v[2:3], v[8:9], v[72:73], v[2:3] op_sel:[0,1,0] op_sel_hi:[1,1,1] neg_lo:[1,0,0] neg_hi:[1,0,0]
	v_pk_fma_f32 v[4:5], v[8:9], v[74:75], v[4:5] op_sel_hi:[1,0,1] neg_lo:[1,0,0] neg_hi:[1,0,0]
	v_pk_fma_f32 v[6:7], v[8:9], v[74:75], v[6:7] op_sel:[0,1,0] op_sel_hi:[1,1,1] neg_lo:[1,0,0] neg_hi:[1,0,0]
	s_waitcnt lgkmcnt(0)
; #define VPKMUL(d, a, b) asm volatile("v_pk_mul_f32 %0, %1, %2" : "=v"(d) : "v"(a), "v"(b))
; __device__ __forceinline__ void scan_half(const Params& p, LAS unsigned char* lds, int pi, int rh, int pass) {
;     ...
;                 LOADREC(0, 0);
;                 float yp = 0.f, yk0 = 0.f, yk1 = 0.f, yk2 = 0.f, yk3 = 0.f;
;     ...
; #pragma unroll
;                 for (int s = 0; s < 32; ++s) {
;                     const int c = s & 1, pc = c ^ 1;
;                     const float si = __int_as_float(__builtin_amdgcn_readlane(__float_as_int(inv2), s));
;                     f32x2 px, py, t01, t23, t45, t67; float x;
;                     f32x2 vv2; vv2.x = Rv[c]; asm volatile("" : "+v"(vv2));
;                     if (s >= 1) {
;                         VPKMUL(px, P01, Rkk[c][0].xy); VPKMUL(py, P01, Rr[pc][0].xy); VPKFMA(px, P23, Rkk[c][0].zw, px); VPKFMA(py, P23, Rr[pc][0].zw, py);
;                         VPKFMA(px, P45, Rkk[c][1].xy, px); VPKFMA(py, P45, Rr[pc][1].xy, py); VPKFMA(px, P67, Rkk[c][1].zw, px); VPKFMA(py, P67, Rr[pc][1].zw, py);
;                         VADD(x, px.x, px.y); VADD(yp, py.x, py.y);
;                     } else {
;                         VPKMUL(px, P01, Rkk[c][0].xy); VPKFMA(px, P23, Rkk[c][0].zw, px); VPKFMA(px, P45, Rkk[c][1].xy, px); VPKFMA(px, P67, Rkk[c][1].zw, px);
;                         VADD(x, px.x, px.y);
;                     }
;                     asm volatile("" ::: "memory");
;                     if (s + 1 < 32) LOADREC((s + 1) & 1, s + 1);
;                     asm volatile("" ::: "memory");
;                     VPKMULBL(t01, vv2, Rkm[c][0].xy); VPKMULBL(t23, vv2, Rkm[c][0].zw);
;                     VDPP1(x); if (s >= 1) VDPP1(yp);
;                     VPKMULBL(t45, vv2, Rkm[c][1].xy); VPKMULBL(t67, vv2, Rkm[c][1].zw);
;                     VDPP2(x); if (s >= 1) VDPP2(yp);
;                     VPKFMA(P01, P01, Rw[c][0].xy, t01); VPKFMA(P23, P23, Rw[c][0].zw, t23);
;                     VDPP3(x); if (s >= 1) VDPP3(yp);
;                     VPKFMA(P45, P45, Rw[c][1].xy, t45); VPKFMA(P67, P67, Rw[c][1].zw, t67);
;                     if (s >= 1) { if (s - 1 < 8) YSHIFT(yk0); else if (s - 1 < 16) YSHIFT(yk1); else if (s - 1 < 24) YSHIFT(yk2); else YSHIFT(yk3); }
;                     x = x * si;
;                     f32x2 x2; x2.x = x; asm volatile("" : "+v"(x2));
	ds_read_b128 v[64:67], v35 offset:1904
	ds_read_b128 v[76:79], v35 offset:28016
	ds_read_b32 v94, v36 offset:896
	ds_read_b32 v95, v38 offset:896
	ds_read_b128 v[68:71], v35 offset:10608
	ds_read_b128 v[72:75], v35 offset:19312
	ds_read_b128 v[84:87], v35 offset:36720
	v_pk_mul_f32 v[8:9], v[0:1], v[48:49] op_sel_hi:[1,0]
	v_pk_mul_f32 v[10:11], v[0:1], v[88:89] op_sel_hi:[1,0]
	v_pk_fma_f32 v[8:9], v[2:3], v[48:49], v[8:9] op_sel:[0,1,0] op_sel_hi:[1,1,1]
	v_pk_fma_f32 v[10:11], v[2:3], v[88:89], v[10:11] op_sel:[0,1,0] op_sel_hi:[1,1,1]
	v_pk_fma_f32 v[8:9], v[4:5], v[50:51], v[8:9] op_sel_hi:[1,0,1]
	v_pk_fma_f32 v[10:11], v[4:5], v[90:91], v[10:11] op_sel_hi:[1,0,1]
	v_pk_fma_f32 v[8:9], v[6:7], v[50:51], v[8:9] op_sel:[0,1,0] op_sel_hi:[1,1,1]
	v_pk_fma_f32 v[10:11], v[6:7], v[90:91], v[10:11] op_sel:[0,1,0] op_sel_hi:[1,1,1]
	v_readlane_b32 s10, v34, 6
	v_pk_mul_f32 v[16:17], v[92:93], v[60:61] op_sel_hi:[1,0]
	v_pk_mul_f32 v[18:19], v[92:93], v[60:61] op_sel:[0,1] op_sel_hi:[1,1]
	v_add_f32_dpp v8, v9, v8 quad_perm:[1,0,3,2] row_mask:0xf bank_mask:0xf bound_ctrl:1
	v_add_f32_dpp v10, v11, v10 quad_perm:[1,0,3,2] row_mask:0xf bank_mask:0xf bound_ctrl:1
	v_pk_mul_f32 v[20:21], v[92:93], v[62:63] op_sel_hi:[1,0]
	v_pk_mul_f32 v[22:23], v[92:93], v[62:63] op_sel:[0,1] op_sel_hi:[1,1]
	v_add_f32_dpp v8, v8, v8 quad_perm:[2,3,0,1] row_mask:0xf bank_mask:0xf bound_ctrl:1
	v_add_f32_dpp v10, v10, v10 quad_perm:[2,3,0,1] row_mask:0xf bank_mask:0xf bound_ctrl:1
	v_pk_fma_f32 v[0:1], v[0:1], v[52:53], v[16:17] op_sel_hi:[1,0,1]
	v_pk_fma_f32 v[2:3], v[2:3], v[52:53], v[18:19] op_sel:[0,1,0] op_sel_hi:[1,1,1]
	v_add_f32_dpp v8, v8, v8 row_ror:4 row_mask:0xf bank_mask:0xf bound_ctrl:1
	v_add_f32_dpp v10, v10, v10 row_ror:4 row_mask:0xf bank_mask:0xf bound_ctrl:1
	v_pk_fma_f32 v[4:5], v[4:5], v[54:55], v[20:21] op_sel_hi:[1,0,1]
	v_add_f32_dpp v8, v8, v8 row_ror:8 row_mask:0xf bank_mask:0xf bound_ctrl:1
	v_mul_f32_e32 v8, s10, v8
	v_add_f32_dpp v97, v10, v10 row_ror:8 row_mask:0xf bank_mask:0x2 bound_ctrl:1
	v_pk_fma_f32 v[6:7], v[6:7], v[54:55], v[22:23] op_sel:[0,1,0] op_sel_hi:[1,1,1]
	v_mov_b32_dpp v9, v8 quad_perm:[1,0,3,2] row_mask:0xf bank_mask:0xf
	v_pk_fma_f32 v[0:1], v[8:9], v[56:57], v[0:1] op_sel_hi:[1,0,1] neg_lo:[1,0,0] neg_hi:[1,0,0]
	v_pk_fma_f32 v[2:3], v[8:9], v[56:57], v[2:3] op_sel:[0,1,0] op_sel_hi:[1,1,1] neg_lo:[1,0,0] neg_hi:[1,0,0]
	v_pk_fma_f32 v[4:5], v[8:9], v[58:59], v[4:5] op_sel_hi:[1,0,1] neg_lo:[1,0,0] neg_hi:[1,0,0]
	v_pk_fma_f32 v[6:7], v[8:9], v[58:59], v[6:7] op_sel:[0,1,0] op_sel_hi:[1,1,1] neg_lo:[1,0,0] neg_hi:[1,0,0]
	s_waitcnt lgkmcnt(0)
	ds_read_b128 v[48:51], v35 offset:2176
	ds_read_b128 v[60:63], v35 offset:28288
	ds_read_b32 v92, v36 offset:1024
	ds_read_b32 v93, v38 offset:1024
	ds_read_b128 v[52:55], v35 offset:10880
	ds_read_b128 v[56:59], v35 offset:19584
	ds_read_b128 v[88:91], v35 offset:36992
	v_pk_mul_f32 v[8:9], v[0:1], v[64:65] op_sel_hi:[1,0]
	v_pk_mul_f32 v[10:11], v[0:1], v[80:81] op_sel_hi:[1,0]
	v_pk_fma_f32 v[8:9], v[2:3], v[64:65], v[8:9] op_sel:[0,1,0] op_sel_hi:[1,1,1]
	v_pk_fma_f32 v[10:11], v[2:3], v[80:81], v[10:11] op_sel:[0,1,0] op_sel_hi:[1,1,1]
	v_pk_fma_f32 v[8:9], v[4:5], v[66:67], v[8:9] op_sel_hi:[1,0,1]
	v_pk_fma_f32 v[10:11], v[4:5], v[82:83], v[10:11] op_sel_hi:[1,0,1]
	v_pk_fma_f32 v[8:9], v[6:7], v[66:67], v[8:9] op_sel:[0,1,0] op_sel_hi:[1,1,1]
	v_pk_fma_f32 v[10:11], v[6:7], v[82:83], v[10:11] op_sel:[0,1,0] op_sel_hi:[1,1,1]
	v_readlane_b32 s10, v34, 7
	v_pk_mul_f32 v[16:17], v[94:95], v[76:77] op_sel_hi:[1,0]
	v_pk_mul_f32 v[18:19], v[94:95], v[76:77] op_sel:[0,1] op_sel_hi:[1,1]
	v_add_f32_dpp v8, v9, v8 quad_perm:[1,0,3,2] row_mask:0xf bank_mask:0xf bound_ctrl:1
	v_add_f32_dpp v10, v11, v10 quad_perm:[1,0,3,2] row_mask:0xf bank_mask:0xf bound_ctrl:1
	v_pk_mul_f32 v[20:21], v[94:95], v[78:79] op_sel_hi:[1,0]
	v_pk_mul_f32 v[22:23], v[94:95], v[78:79] op_sel:[0,1] op_sel_hi:[1,1]
	v_add_f32_dpp v8, v8, v8 quad_perm:[2,3,0,1] row_mask:0xf bank_mask:0xf bound_ctrl:1
	v_add_f32_dpp v10, v10, v10 quad_perm:[2,3,0,1] row_mask:0xf bank_mask:0xf bound_ctrl:1
	v_pk_fma_f32 v[0:1], v[0:1], v[68:69], v[16:17] op_sel_hi:[1,0,1]
	v_pk_fma_f32 v[2:3], v[2:3], v[68:69], v[18:19] op_sel:[0,1,0] op_sel_hi:[1,1,1]
	v_add_f32_dpp v8, v8, v8 row_ror:4 row_mask:0xf bank_mask:0xf bound_ctrl:1
	v_add_f32_dpp v10, v10, v10 row_ror:4 row_mask:0xf bank_mask:0xf bound_ctrl:1
	v_pk_fma_f32 v[4:5], v[4:5], v[70:71], v[20:21] op_sel_hi:[1,0,1]
	v_add_f32_dpp v8, v8, v8 row_ror:8 row_mask:0xf bank_mask:0xf bound_ctrl:1
	v_mul_f32_e32 v8, s10, v8
	v_add_f32_dpp v97, v10, v10 row_ror:8 row_mask:0xf bank_mask:0x4 bound_ctrl:1
	v_pk_fma_f32 v[6:7], v[6:7], v[70:71], v[22:23] op_sel:[0,1,0] op_sel_hi:[1,1,1]
	v_mov_b32_dpp v9, v8 quad_perm:[1,0,3,2] row_mask:0xf bank_mask:0xf
	v_pk_fma_f32 v[0:1], v[8:9], v[72:73], v[0:1] op_sel_hi:[1,0,1] neg_lo:[1,0,0] neg_hi:[1,0,0]
	v_pk_fma_f32 v[2:3], v[8:9], v[72:73], v[2:3] op_sel:[0,1,0] op_sel_hi:[1,1,1] neg_lo:[1,0,0] neg_hi:[1,0,0]
	v_pk_fma_f32 v[4:5], v[8:9], v[74:75], v[4:5] op_sel_hi:[1,0,1] neg_lo:[1,0,0] neg_hi:[1,0,0]
	v_pk_fma_f32 v[6:7], v[8:9], v[74:75], v[6:7] op_sel:[0,1,0] op_sel_hi:[1,1,1] neg_lo:[1,0,0] neg_hi:[1,0,0]
	s_waitcnt lgkmcnt(0)
; #define VPKMUL(d, a, b) asm volatile("v_pk_mul_f32 %0, %1, %2" : "=v"(d) : "v"(a), "v"(b))
; __device__ __forceinline__ void scan_half(const Params& p, LAS unsigned char* lds, int pi, int rh, int pass) {
;     ...
;                 LOADREC(0, 0);
;                 float yp = 0.f, yk0 = 0.f, yk1 = 0.f, yk2 = 0.f, yk3 = 0.f;
;     ...
; #pragma unroll
;                 for (int s = 0; s < 32; ++s) {
;                     const int c = s & 1, pc = c ^ 1;
;                     const float si = __int_as_float(__builtin_amdgcn_readlane(__float_as_int(inv2), s));
;                     f32x2 px, py, t01, t23, t45, t67; float x;
;                     f32x2 vv2; vv2.x = Rv[c]; asm volatile("" : "+v"(vv2));
;                     if (s >= 1) {
;                         VPKMUL(px, P01, Rkk[c][0].xy); VPKMUL(py, P01, Rr[pc][0].xy); VPKFMA(px, P23, Rkk[c][0].zw, px); VPKFMA(py, P23, Rr[pc][0].zw, py);
;                         VPKFMA(px, P45, Rkk[c][1].xy, px); VPKFMA(py, P45, Rr[pc][1].xy, py); VPKFMA(px, P67, Rkk[c][1].zw, px); VPKFMA(py, P67, Rr[pc][1].zw, py);
;                         VADD(x, px.x, px.y); VADD(yp, py.x, py.y);
;                     } else {
;                         VPKMUL(px, P01, Rkk[c][0].xy); VPKFMA(px, P23, Rkk[c][0].zw, px); VPKFMA(px, P45, Rkk[c][1].xy, px); VPKFMA(px, P67, Rkk[c][1].zw, px);
;                         VADD(x, px.x, px.y);
;                     }
;                     asm volatile("" ::: "memory");
;                     if (s + 1 < 32) LOADREC((s + 1) & 1, s + 1);
;                     asm volatile("" ::: "memory");
;                     VPKMULBL(t01, vv2, Rkm[c][0].xy); VPKMULBL(t23, vv2, Rkm[c][0].zw);
;                     VDPP1(x); if (s >= 1) VDPP1(yp);
;                     VPKMULBL(t45, vv2, Rkm[c][1].xy); VPKMULBL(t67, vv2, Rkm[c][1].zw);
;                     VDPP2(x); if (s >= 1) VDPP2(yp);
;                     VPKFMA(P01, P01, Rw[c][0].xy, t01); VPKFMA(P23, P23, Rw[c][0].zw, t23);
;                     VDPP3(x); if (s >= 1) VDPP3(yp);
;                     VPKFMA(P45, P45, Rw[c][1].xy, t45); VPKFMA(P67, P67, Rw[c][1].zw, t67);
;                     if (s >= 1) { if (s - 1 < 8) YSHIFT(yk0); else if (s - 1 < 16) YSHIFT(yk1); else if (s - 1 < 24) YSHIFT(yk2); else YSHIFT(yk3); }
;                     x = x * si;
;                     f32x2 x2; x2.x = x; asm volatile("" : "+v"(x2));
	ds_read_b128 v[64:67], v35 offset:2448
	ds_read_b128 v[76:79], v35 offset:28560
	ds_read_b32 v94, v36 offset:1152
	ds_read_b32 v95, v38 offset:1152
	ds_read_b128 v[68:71], v35 offset:11152
	ds_read_b128 v[72:75], v35 offset:19856
	ds_read_b128 v[80:83], v35 offset:37264
	v_pk_mul_f32 v[8:9], v[0:1], v[48:49] op_sel_hi:[1,0]
	v_pk_mul_f32 v[10:11], v[0:1], v[84:85] op_sel_hi:[1,0]
	v_pk_fma_f32 v[8:9], v[2:3], v[48:49], v[8:9] op_sel:[0,1,0] op_sel_hi:[1,1,1]
	v_pk_fma_f32 v[10:11], v[2:3], v[84:85], v[10:11] op_sel:[0,1,0] op_sel_hi:[1,1,1]
	v_pk_fma_f32 v[8:9], v[4:5], v[50:51], v[8:9] op_sel_hi:[1,0,1]
	v_pk_fma_f32 v[10:11], v[4:5], v[86:87], v[10:11] op_sel_hi:[1,0,1]
	v_pk_fma_f32 v[8:9], v[6:7], v[50:51], v[8:9] op_sel:[0,1,0] op_sel_hi:[1,1,1]
	v_pk_fma_f32 v[10:11], v[6:7], v[86:87], v[10:11] op_sel:[0,1,0] op_sel_hi:[1,1,1]
	v_readlane_b32 s10, v34, 8
	v_pk_mul_f32 v[16:17], v[92:93], v[60:61] op_sel_hi:[1,0]
	v_pk_mul_f32 v[18:19], v[92:93], v[60:61] op_sel:[0,1] op_sel_hi:[1,1]
	v_add_f32_dpp v8, v9, v8 quad_perm:[1,0,3,2] row_mask:0xf bank_mask:0xf bound_ctrl:1
	v_add_f32_dpp v10, v11, v10 quad_perm:[1,0,3,2] row_mask:0xf bank_mask:0xf bound_ctrl:1
	v_pk_mul_f32 v[20:21], v[92:93], v[62:63] op_sel_hi:[1,0]
	v_pk_mul_f32 v[22:23], v[92:93], v[62:63] op_sel:[0,1] op_sel_hi:[1,1]
	v_add_f32_dpp v8, v8, v8 quad_perm:[2,3,0,1] row_mask:0xf bank_mask:0xf bound_ctrl:1
	v_add_f32_dpp v10, v10, v10 quad_perm:[2,3,0,1] row_mask:0xf bank_mask:0xf bound_ctrl:1
	v_pk_fma_f32 v[0:1], v[0:1], v[52:53], v[16:17] op_sel_hi:[1,0,1]
	v_pk_fma_f32 v[2:3], v[2:3], v[52:53], v[18:19] op_sel:[0,1,0] op_sel_hi:[1,1,1]
	v_add_f32_dpp v8, v8, v8 row_ror:4 row_mask:0xf bank_mask:0xf bound_ctrl:1
	v_add_f32_dpp v10, v10, v10 row_ror:4 row_mask:0xf bank_mask:0xf bound_ctrl:1
	v_pk_fma_f32 v[4:5], v[4:5], v[54:55], v[20:21] op_sel_hi:[1,0,1]
	v_add_f32_dpp v8, v8, v8 row_ror:8 row_mask:0xf bank_mask:0xf bound_ctrl:1
	v_mul_f32_e32 v8, s10, v8
	v_add_f32_dpp v97, v10, v10 row_ror:8 row_mask:0xf bank_mask:0x8 bound_ctrl:1
	v_pk_fma_f32 v[6:7], v[6:7], v[54:55], v[22:23] op_sel:[0,1,0] op_sel_hi:[1,1,1]
	v_mov_b32_dpp v9, v8 quad_perm:[1,0,3,2] row_mask:0xf bank_mask:0xf
	v_pk_fma_f32 v[0:1], v[8:9], v[56:57], v[0:1] op_sel_hi:[1,0,1] neg_lo:[1,0,0] neg_hi:[1,0,0]
	v_pk_fma_f32 v[2:3], v[8:9], v[56:57], v[2:3] op_sel:[0,1,0] op_sel_hi:[1,1,1] neg_lo:[1,0,0] neg_hi:[1,0,0]
	v_pk_fma_f32 v[4:5], v[8:9], v[58:59], v[4:5] op_sel_hi:[1,0,1] neg_lo:[1,0,0] neg_hi:[1,0,0]
	v_pk_fma_f32 v[6:7], v[8:9], v[58:59], v[6:7] op_sel:[0,1,0] op_sel_hi:[1,1,1] neg_lo:[1,0,0] neg_hi:[1,0,0]
	s_waitcnt lgkmcnt(0)
	ds_read_b128 v[48:51], v35 offset:2720
	ds_read_b128 v[60:63], v35 offset:28832
	ds_read_b32 v92, v36 offset:1280
	ds_read_b32 v93, v38 offset:1280
	ds_read_b128 v[52:55], v35 offset:11424
	ds_read_b128 v[56:59], v35 offset:20128
	ds_read_b128 v[84:87], v35 offset:37536
	v_pk_mul_f32 v[8:9], v[0:1], v[64:65] op_sel_hi:[1,0]
	v_pk_mul_f32 v[10:11], v[0:1], v[88:89] op_sel_hi:[1,0]
	v_pk_fma_f32 v[8:9], v[2:3], v[64:65], v[8:9] op_sel:[0,1,0] op_sel_hi:[1,1,1]
	v_pk_fma_f32 v[10:11], v[2:3], v[88:89], v[10:11] op_sel:[0,1,0] op_sel_hi:[1,1,1]
	v_pk_fma_f32 v[8:9], v[4:5], v[66:67], v[8:9] op_sel_hi:[1,0,1]
	v_pk_fma_f32 v[10:11], v[4:5], v[90:91], v[10:11] op_sel_hi:[1,0,1]
	v_pk_fma_f32 v[8:9], v[6:7], v[66:67], v[8:9] op_sel:[0,1,0] op_sel_hi:[1,1,1]
	v_pk_fma_f32 v[10:11], v[6:7], v[90:91], v[10:11] op_sel:[0,1,0] op_sel_hi:[1,1,1]
	v_readlane_b32 s10, v34, 9
	v_pk_mul_f32 v[16:17], v[94:95], v[76:77] op_sel_hi:[1,0]
	v_pk_mul_f32 v[18:19], v[94:95], v[76:77] op_sel:[0,1] op_sel_hi:[1,1]
	v_add_f32_dpp v8, v9, v8 quad_perm:[1,0,3,2] row_mask:0xf bank_mask:0xf bound_ctrl:1
	v_add_f32_dpp v10, v11, v10 quad_perm:[1,0,3,2] row_mask:0xf bank_mask:0xf bound_ctrl:1
	v_pk_mul_f32 v[20:21], v[94:95], v[78:79] op_sel_hi:[1,0]
	v_pk_mul_f32 v[22:23], v[94:95], v[78:79] op_sel:[0,1] op_sel_hi:[1,1]
	v_add_f32_dpp v8, v8, v8 quad_perm:[2,3,0,1] row_mask:0xf bank_mask:0xf bound_ctrl:1
	v_add_f32_dpp v10, v10, v10 quad_perm:[2,3,0,1] row_mask:0xf bank_mask:0xf bound_ctrl:1
	v_pk_fma_f32 v[0:1], v[0:1], v[68:69], v[16:17] op_sel_hi:[1,0,1]
	v_pk_fma_f32 v[2:3], v[2:3], v[68:69], v[18:19] op_sel:[0,1,0] op_sel_hi:[1,1,1]
	v_add_f32_dpp v8, v8, v8 row_ror:4 row_mask:0xf bank_mask:0xf bound_ctrl:1
	v_add_f32_dpp v10, v10, v10 row_ror:4 row_mask:0xf bank_mask:0xf bound_ctrl:1
	v_pk_fma_f32 v[4:5], v[4:5], v[70:71], v[20:21] op_sel_hi:[1,0,1]
	v_add_f32_dpp v8, v8, v8 row_ror:8 row_mask:0xf bank_mask:0xf bound_ctrl:1
	v_mul_f32_e32 v8, s10, v8
	v_add_f32_dpp v98, v10, v10 row_ror:8 row_mask:0xf bank_mask:0x1 bound_ctrl:1
	v_pk_fma_f32 v[6:7], v[6:7], v[70:71], v[22:23] op_sel:[0,1,0] op_sel_hi:[1,1,1]
	v_mov_b32_dpp v9, v8 quad_perm:[1,0,3,2] row_mask:0xf bank_mask:0xf
	v_pk_fma_f32 v[0:1], v[8:9], v[72:73], v[0:1] op_sel_hi:[1,0,1] neg_lo:[1,0,0] neg_hi:[1,0,0]
	v_pk_fma_f32 v[2:3], v[8:9], v[72:73], v[2:3] op_sel:[0,1,0] op_sel_hi:[1,1,1] neg_lo:[1,0,0] neg_hi:[1,0,0]
	v_pk_fma_f32 v[4:5], v[8:9], v[74:75], v[4:5] op_sel_hi:[1,0,1] neg_lo:[1,0,0] neg_hi:[1,0,0]
	v_pk_fma_f32 v[6:7], v[8:9], v[74:75], v[6:7] op_sel:[0,1,0] op_sel_hi:[1,1,1] neg_lo:[1,0,0] neg_hi:[1,0,0]
	s_waitcnt lgkmcnt(0)
; #define VPKMUL(d, a, b) asm volatile("v_pk_mul_f32 %0, %1, %2" : "=v"(d) : "v"(a), "v"(b))
; __device__ __forceinline__ void scan_half(const Params& p, LAS unsigned char* lds, int pi, int rh, int pass) {
;     ...
;                 LOADREC(0, 0);
;                 float yp = 0.f, yk0 = 0.f, yk1 = 0.f, yk2 = 0.f, yk3 = 0.f;
;     ...
; #pragma unroll
;                 for (int s = 0; s < 32; ++s) {
;                     const int c = s & 1, pc = c ^ 1;
;                     const float si = __int_as_float(__builtin_amdgcn_readlane(__float_as_int(inv2), s));
;                     f32x2 px, py, t01, t23, t45, t67; float x;
;                     f32x2 vv2; vv2.x = Rv[c]; asm volatile("" : "+v"(vv2));
;                     if (s >= 1) {
;                         VPKMUL(px, P01, Rkk[c][0].xy); VPKMUL(py, P01, Rr[pc][0].xy); VPKFMA(px, P23, Rkk[c][0].zw, px); VPKFMA(py, P23, Rr[pc][0].zw, py);
;                         VPKFMA(px, P45, Rkk[c][1].xy, px); VPKFMA(py, P45, Rr[pc][1].xy, py); VPKFMA(px, P67, Rkk[c][1].zw, px); VPKFMA(py, P67, Rr[pc][1].zw, py);
;                         VADD(x, px.x, px.y); VADD(yp, py.x, py.y);
;                     } else {
;                         VPKMUL(px, P01, Rkk[c][0].xy); VPKFMA(px, P23, Rkk[c][0].zw, px); VPKFMA(px, P45, Rkk[c][1].xy, px); VPKFMA(px, P67, Rkk[c][1].zw, px);
;                         VADD(x, px.x, px.y);
;                     }
;                     asm volatile("" ::: "memory");
;                     if (s + 1 < 32) LOADREC((s + 1) & 1, s + 1);
;                     asm volatile("" ::: "memory");
;                     VPKMULBL(t01, vv2, Rkm[c][0].xy); VPKMULBL(t23, vv2, Rkm[c][0].zw);
;                     VDPP1(x); if (s >= 1) VDPP1(yp);
;                     VPKMULBL(t45, vv2, Rkm[c][1].xy); VPKMULBL(t67, vv2, Rkm[c][1].zw);
;                     VDPP2(x); if (s >= 1) VDPP2(yp);
;                     VPKFMA(P01, P01, Rw[c][0].xy, t01); VPKFMA(P23, P23, Rw[c][0].zw, t23);
;                     VDPP3(x); if (s >= 1) VDPP3(yp);
;                     VPKFMA(P45, P45, Rw[c][1].xy, t45); VPKFMA(P67, P67, Rw[c][1].zw, t67);
;                     if (s >= 1) { if (s - 1 < 8) YSHIFT(yk0); else if (s - 1 < 16) YSHIFT(yk1); else if (s - 1 < 24) YSHIFT(yk2); else YSHIFT(yk3); }
;                     x = x * si;
;                     f32x2 x2; x2.x = x; asm volatile("" : "+v"(x2));
	ds_read_b128 v[64:67], v35 offset:2992
	ds_read_b128 v[76:79], v35 offset:29104
	ds_read_b32 v94, v36 offset:1408
	ds_read_b32 v95, v38 offset:1408
	ds_read_b128 v[68:71], v35 offset:11696
	ds_read_b128 v[72:75], v35 offset:20400
	ds_read_b128 v[88:91], v35 offset:37808
	v_pk_mul_f32 v[8:9], v[0:1], v[48:49] op_sel_hi:[1,0]
	v_pk_mul_f32 v[10:11], v[0:1], v[80:81] op_sel_hi:[1,0]
	v_pk_fma_f32 v[8:9], v[2:3], v[48:49], v[8:9] op_sel:[0,1,0] op_sel_hi:[1,1,1]
	v_pk_fma_f32 v[10:11], v[2:3], v[80:81], v[10:11] op_sel:[0,1,0] op_sel_hi:[1,1,1]
	v_pk_fma_f32 v[8:9], v[4:5], v[50:51], v[8:9] op_sel_hi:[1,0,1]
	v_pk_fma_f32 v[10:11], v[4:5], v[82:83], v[10:11] op_sel_hi:[1,0,1]
	v_pk_fma_f32 v[8:9], v[6:7], v[50:51], v[8:9] op_sel:[0,1,0] op_sel_hi:[1,1,1]
	v_pk_fma_f32 v[10:11], v[6:7], v[82:83], v[10:11] op_sel:[0,1,0] op_sel_hi:[1,1,1]
	v_readlane_b32 s10, v34, 10
	v_pk_mul_f32 v[16:17], v[92:93], v[60:61] op_sel_hi:[1,0]
	v_pk_mul_f32 v[18:19], v[92:93], v[60:61] op_sel:[0,1] op_sel_hi:[1,1]
	v_add_f32_dpp v8, v9, v8 quad_perm:[1,0,3,2] row_mask:0xf bank_mask:0xf bound_ctrl:1
	v_add_f32_dpp v10, v11, v10 quad_perm:[1,0,3,2] row_mask:0xf bank_mask:0xf bound_ctrl:1
	v_pk_mul_f32 v[20:21], v[92:93], v[62:63] op_sel_hi:[1,0]
	v_pk_mul_f32 v[22:23], v[92:93], v[62:63] op_sel:[0,1] op_sel_hi:[1,1]
	v_add_f32_dpp v8, v8, v8 quad_perm:[2,3,0,1] row_mask:0xf bank_mask:0xf bound_ctrl:1
	v_add_f32_dpp v10, v10, v10 quad_perm:[2,3,0,1] row_mask:0xf bank_mask:0xf bound_ctrl:1
	v_pk_fma_f32 v[0:1], v[0:1], v[52:53], v[16:17] op_sel_hi:[1,0,1]
	v_pk_fma_f32 v[2:3], v[2:3], v[52:53], v[18:19] op_sel:[0,1,0] op_sel_hi:[1,1,1]
	v_add_f32_dpp v8, v8, v8 row_ror:4 row_mask:0xf bank_mask:0xf bound_ctrl:1
	v_add_f32_dpp v10, v10, v10 row_ror:4 row_mask:0xf bank_mask:0xf bound_ctrl:1
	v_pk_fma_f32 v[4:5], v[4:5], v[54:55], v[20:21] op_sel_hi:[1,0,1]
	v_add_f32_dpp v8, v8, v8 row_ror:8 row_mask:0xf bank_mask:0xf bound_ctrl:1
	v_mul_f32_e32 v8, s10, v8
	v_add_f32_dpp v98, v10, v10 row_ror:8 row_mask:0xf bank_mask:0x2 bound_ctrl:1
	v_pk_fma_f32 v[6:7], v[6:7], v[54:55], v[22:23] op_sel:[0,1,0] op_sel_hi:[1,1,1]
	v_mov_b32_dpp v9, v8 quad_perm:[1,0,3,2] row_mask:0xf bank_mask:0xf
	v_pk_fma_f32 v[0:1], v[8:9], v[56:57], v[0:1] op_sel_hi:[1,0,1] neg_lo:[1,0,0] neg_hi:[1,0,0]
	v_pk_fma_f32 v[2:3], v[8:9], v[56:57], v[2:3] op_sel:[0,1,0] op_sel_hi:[1,1,1] neg_lo:[1,0,0] neg_hi:[1,0,0]
	v_pk_fma_f32 v[4:5], v[8:9], v[58:59], v[4:5] op_sel_hi:[1,0,1] neg_lo:[1,0,0] neg_hi:[1,0,0]
	v_pk_fma_f32 v[6:7], v[8:9], v[58:59], v[6:7] op_sel:[0,1,0] op_sel_hi:[1,1,1] neg_lo:[1,0,0] neg_hi:[1,0,0]
	s_waitcnt lgkmcnt(0)
	ds_read_b128 v[48:51], v35 offset:3264
	ds_read_b128 v[60:63], v35 offset:29376
	ds_read_b32 v92, v36 offset:1536
	ds_read_b32 v93, v38 offset:1536
	ds_read_b128 v[52:55], v35 offset:11968
	ds_read_b128 v[56:59], v35 offset:20672
	ds_read_b128 v[80:83], v35 offset:38080
	v_pk_mul_f32 v[8:9], v[0:1], v[64:65] op_sel_hi:[1,0]
	v_pk_mul_f32 v[10:11], v[0:1], v[84:85] op_sel_hi:[1,0]
	v_pk_fma_f32 v[8:9], v[2:3], v[64:65], v[8:9] op_sel:[0,1,0] op_sel_hi:[1,1,1]
	v_pk_fma_f32 v[10:11], v[2:3], v[84:85], v[10:11] op_sel:[0,1,0] op_sel_hi:[1,1,1]
	v_pk_fma_f32 v[8:9], v[4:5], v[66:67], v[8:9] op_sel_hi:[1,0,1]
	v_pk_fma_f32 v[10:11], v[4:5], v[86:87], v[10:11] op_sel_hi:[1,0,1]
	v_pk_fma_f32 v[8:9], v[6:7], v[66:67], v[8:9] op_sel:[0,1,0] op_sel_hi:[1,1,1]
	v_pk_fma_f32 v[10:11], v[6:7], v[86:87], v[10:11] op_sel:[0,1,0] op_sel_hi:[1,1,1]
	v_readlane_b32 s10, v34, 11
	v_pk_mul_f32 v[16:17], v[94:95], v[76:77] op_sel_hi:[1,0]
	v_pk_mul_f32 v[18:19], v[94:95], v[76:77] op_sel:[0,1] op_sel_hi:[1,1]
	v_add_f32_dpp v8, v9, v8 quad_perm:[1,0,3,2] row_mask:0xf bank_mask:0xf bound_ctrl:1
	v_add_f32_dpp v10, v11, v10 quad_perm:[1,0,3,2] row_mask:0xf bank_mask:0xf bound_ctrl:1
	v_pk_mul_f32 v[20:21], v[94:95], v[78:79] op_sel_hi:[1,0]
	v_pk_mul_f32 v[22:23], v[94:95], v[78:79] op_sel:[0,1] op_sel_hi:[1,1]
	v_add_f32_dpp v8, v8, v8 quad_perm:[2,3,0,1] row_mask:0xf bank_mask:0xf bound_ctrl:1
	v_add_f32_dpp v10, v10, v10 quad_perm:[2,3,0,1] row_mask:0xf bank_mask:0xf bound_ctrl:1
	v_pk_fma_f32 v[0:1], v[0:1], v[68:69], v[16:17] op_sel_hi:[1,0,1]
	v_pk_fma_f32 v[2:3], v[2:3], v[68:69], v[18:19] op_sel:[0,1,0] op_sel_hi:[1,1,1]
	v_add_f32_dpp v8, v8, v8 row_ror:4 row_mask:0xf bank_mask:0xf bound_ctrl:1
	v_add_f32_dpp v10, v10, v10 row_ror:4 row_mask:0xf bank_mask:0xf bound_ctrl:1
	v_pk_fma_f32 v[4:5], v[4:5], v[70:71], v[20:21] op_sel_hi:[1,0,1]
	v_add_f32_dpp v8, v8, v8 row_ror:8 row_mask:0xf bank_mask:0xf bound_ctrl:1
	v_mul_f32_e32 v8, s10, v8
	v_add_f32_dpp v98, v10, v10 row_ror:8 row_mask:0xf bank_mask:0x4 bound_ctrl:1
	v_pk_fma_f32 v[6:7], v[6:7], v[70:71], v[22:23] op_sel:[0,1,0] op_sel_hi:[1,1,1]
	v_mov_b32_dpp v9, v8 quad_perm:[1,0,3,2] row_mask:0xf bank_mask:0xf
	v_pk_fma_f32 v[0:1], v[8:9], v[72:73], v[0:1] op_sel_hi:[1,0,1] neg_lo:[1,0,0] neg_hi:[1,0,0]
	v_pk_fma_f32 v[2:3], v[8:9], v[72:73], v[2:3] op_sel:[0,1,0] op_sel_hi:[1,1,1] neg_lo:[1,0,0] neg_hi:[1,0,0]
	v_pk_fma_f32 v[4:5], v[8:9], v[74:75], v[4:5] op_sel_hi:[1,0,1] neg_lo:[1,0,0] neg_hi:[1,0,0]
	v_pk_fma_f32 v[6:7], v[8:9], v[74:75], v[6:7] op_sel:[0,1,0] op_sel_hi:[1,1,1] neg_lo:[1,0,0] neg_hi:[1,0,0]
	s_waitcnt lgkmcnt(0)
; #define VPKMUL(d, a, b) asm volatile("v_pk_mul_f32 %0, %1, %2" : "=v"(d) : "v"(a), "v"(b))
; __device__ __forceinline__ void scan_half(const Params& p, LAS unsigned char* lds, int pi, int rh, int pass) {
;     ...
;                 LOADREC(0, 0);
;                 float yp = 0.f, yk0 = 0.f, yk1 = 0.f, yk2 = 0.f, yk3 = 0.f;
;     ...
; #pragma unroll
;                 for (int s = 0; s < 32; ++s) {
;                     const int c = s & 1, pc = c ^ 1;
;                     const float si = __int_as_float(__builtin_amdgcn_readlane(__float_as_int(inv2), s));
;                     f32x2 px, py, t01, t23, t45, t67; float x;
;                     f32x2 vv2; vv2.x = Rv[c]; asm volatile("" : "+v"(vv2));
;                     if (s >= 1) {
;                         VPKMUL(px, P01, Rkk[c][0].xy); VPKMUL(py, P01, Rr[pc][0].xy); VPKFMA(px, P23, Rkk[c][0].zw, px); VPKFMA(py, P23, Rr[pc][0].zw, py);
;                         VPKFMA(px, P45, Rkk[c][1].xy, px); VPKFMA(py, P45, Rr[pc][1].xy, py); VPKFMA(px, P67, Rkk[c][1].zw, px); VPKFMA(py, P67, Rr[pc][1].zw, py);
;                         VADD(x, px.x, px.y); VADD(yp, py.x, py.y);
;                     } else {
;                         VPKMUL(px, P01, Rkk[c][0].xy); VPKFMA(px, P23, Rkk[c][0].zw, px); VPKFMA(px, P45, Rkk[c][1].xy, px); VPKFMA(px, P67, Rkk[c][1].zw, px);
;                         VADD(x, px.x, px.y);
;                     }
;                     asm volatile("" ::: "memory");
;                     if (s + 1 < 32) LOADREC((s + 1) & 1, s + 1);
;                     asm volatile("" ::: "memory");
;                     VPKMULBL(t01, vv2, Rkm[c][0].xy); VPKMULBL(t23, vv2, Rkm[c][0].zw);
;                     VDPP1(x); if (s >= 1) VDPP1(yp);
;                     VPKMULBL(t45, vv2, Rkm[c][1].xy); VPKMULBL(t67, vv2, Rkm[c][1].zw);
;                     VDPP2(x); if (s >= 1) VDPP2(yp);
;                     VPKFMA(P01, P01, Rw[c][0].xy, t01); VPKFMA(P23, P23, Rw[c][0].zw, t23);
;                     VDPP3(x); if (s >= 1) VDPP3(yp);
;                     VPKFMA(P45, P45, Rw[c][1].xy, t45); VPKFMA(P67, P67, Rw[c][1].zw, t67);
;                     if (s >= 1) { if (s - 1 < 8) YSHIFT(yk0); else if (s - 1 < 16) YSHIFT(yk1); else if (s - 1 < 24) YSHIFT(yk2); else YSHIFT(yk3); }
;                     x = x * si;
;                     f32x2 x2; x2.x = x; asm volatile("" : "+v"(x2));
	ds_read_b128 v[64:67], v35 offset:3536
	ds_read_b128 v[76:79], v35 offset:29648
	ds_read_b32 v94, v36 offset:1664
	ds_read_b32 v95, v38 offset:1664
	ds_read_b128 v[68:71], v35 offset:12240
	ds_read_b128 v[72:75], v35 offset:20944
	ds_read_b128 v[84:87], v35 offset:38352
	v_pk_mul_f32 v[8:9], v[0:1], v[48:49] op_sel_hi:[1,0]
	v_pk_mul_f32 v[10:11], v[0:1], v[88:89] op_sel_hi:[1,0]
	v_pk_fma_f32 v[8:9], v[2:3], v[48:49], v[8:9] op_sel:[0,1,0] op_sel_hi:[1,1,1]
	v_pk_fma_f32 v[10:11], v[2:3], v[88:89], v[10:11] op_sel:[0,1,0] op_sel_hi:[1,1,1]
	v_pk_fma_f32 v[8:9], v[4:5], v[50:51], v[8:9] op_sel_hi:[1,0,1]
	v_pk_fma_f32 v[10:11], v[4:5], v[90:91], v[10:11] op_sel_hi:[1,0,1]
	v_pk_fma_f32 v[8:9], v[6:7], v[50:51], v[8:9] op_sel:[0,1,0] op_sel_hi:[1,1,1]
	v_pk_fma_f32 v[10:11], v[6:7], v[90:91], v[10:11] op_sel:[0,1,0] op_sel_hi:[1,1,1]
	v_readlane_b32 s10, v34, 12
	v_pk_mul_f32 v[16:17], v[92:93], v[60:61] op_sel_hi:[1,0]
	v_pk_mul_f32 v[18:19], v[92:93], v[60:61] op_sel:[0,1] op_sel_hi:[1,1]
	v_add_f32_dpp v8, v9, v8 quad_perm:[1,0,3,2] row_mask:0xf bank_mask:0xf bound_ctrl:1
	v_add_f32_dpp v10, v11, v10 quad_perm:[1,0,3,2] row_mask:0xf bank_mask:0xf bound_ctrl:1
	v_pk_mul_f32 v[20:21], v[92:93], v[62:63] op_sel_hi:[1,0]
	v_pk_mul_f32 v[22:23], v[92:93], v[62:63] op_sel:[0,1] op_sel_hi:[1,1]
	v_add_f32_dpp v8, v8, v8 quad_perm:[2,3,0,1] row_mask:0xf bank_mask:0xf bound_ctrl:1
	v_add_f32_dpp v10, v10, v10 quad_perm:[2,3,0,1] row_mask:0xf bank_mask:0xf bound_ctrl:1
	v_pk_fma_f32 v[0:1], v[0:1], v[52:53], v[16:17] op_sel_hi:[1,0,1]
	v_pk_fma_f32 v[2:3], v[2:3], v[52:53], v[18:19] op_sel:[0,1,0] op_sel_hi:[1,1,1]
	v_add_f32_dpp v8, v8, v8 row_ror:4 row_mask:0xf bank_mask:0xf bound_ctrl:1
	v_add_f32_dpp v10, v10, v10 row_ror:4 row_mask:0xf bank_mask:0xf bound_ctrl:1
	v_pk_fma_f32 v[4:5], v[4:5], v[54:55], v[20:21] op_sel_hi:[1,0,1]
	v_add_f32_dpp v8, v8, v8 row_ror:8 row_mask:0xf bank_mask:0xf bound_ctrl:1
	v_mul_f32_e32 v8, s10, v8
	v_add_f32_dpp v98, v10, v10 row_ror:8 row_mask:0xf bank_mask:0x8 bound_ctrl:1
	v_pk_fma_f32 v[6:7], v[6:7], v[54:55], v[22:23] op_sel:[0,1,0] op_sel_hi:[1,1,1]
	v_mov_b32_dpp v9, v8 quad_perm:[1,0,3,2] row_mask:0xf bank_mask:0xf
	v_pk_fma_f32 v[0:1], v[8:9], v[56:57], v[0:1] op_sel_hi:[1,0,1] neg_lo:[1,0,0] neg_hi:[1,0,0]
	v_pk_fma_f32 v[2:3], v[8:9], v[56:57], v[2:3] op_sel:[0,1,0] op_sel_hi:[1,1,1] neg_lo:[1,0,0] neg_hi:[1,0,0]
	v_pk_fma_f32 v[4:5], v[8:9], v[58:59], v[4:5] op_sel_hi:[1,0,1] neg_lo:[1,0,0] neg_hi:[1,0,0]
	v_pk_fma_f32 v[6:7], v[8:9], v[58:59], v[6:7] op_sel:[0,1,0] op_sel_hi:[1,1,1] neg_lo:[1,0,0] neg_hi:[1,0,0]
	s_waitcnt lgkmcnt(0)
	ds_read_b128 v[48:51], v35 offset:3808
	ds_read_b128 v[60:63], v35 offset:29920
	ds_read_b32 v92, v36 offset:1792
	ds_read_b32 v93, v38 offset:1792
	ds_read_b128 v[52:55], v35 offset:12512
	ds_read_b128 v[56:59], v35 offset:21216
	ds_read_b128 v[88:91], v35 offset:38624
	v_pk_mul_f32 v[8:9], v[0:1], v[64:65] op_sel_hi:[1,0]
	v_pk_mul_f32 v[10:11], v[0:1], v[80:81] op_sel_hi:[1,0]
	v_pk_fma_f32 v[8:9], v[2:3], v[64:65], v[8:9] op_sel:[0,1,0] op_sel_hi:[1,1,1]
	v_pk_fma_f32 v[10:11], v[2:3], v[80:81], v[10:11] op_sel:[0,1,0] op_sel_hi:[1,1,1]
	v_pk_fma_f32 v[8:9], v[4:5], v[66:67], v[8:9] op_sel_hi:[1,0,1]
	v_pk_fma_f32 v[10:11], v[4:5], v[82:83], v[10:11] op_sel_hi:[1,0,1]
	v_pk_fma_f32 v[8:9], v[6:7], v[66:67], v[8:9] op_sel:[0,1,0] op_sel_hi:[1,1,1]
	v_pk_fma_f32 v[10:11], v[6:7], v[82:83], v[10:11] op_sel:[0,1,0] op_sel_hi:[1,1,1]
	v_readlane_b32 s10, v34, 13
	v_pk_mul_f32 v[16:17], v[94:95], v[76:77] op_sel_hi:[1,0]
	v_pk_mul_f32 v[18:19], v[94:95], v[76:77] op_sel:[0,1] op_sel_hi:[1,1]
	v_add_f32_dpp v8, v9, v8 quad_perm:[1,0,3,2] row_mask:0xf bank_mask:0xf bound_ctrl:1
	v_add_f32_dpp v10, v11, v10 quad_perm:[1,0,3,2] row_mask:0xf bank_mask:0xf bound_ctrl:1
	v_pk_mul_f32 v[20:21], v[94:95], v[78:79] op_sel_hi:[1,0]
	v_pk_mul_f32 v[22:23], v[94:95], v[78:79] op_sel:[0,1] op_sel_hi:[1,1]
	v_add_f32_dpp v8, v8, v8 quad_perm:[2,3,0,1] row_mask:0xf bank_mask:0xf bound_ctrl:1
	v_add_f32_dpp v10, v10, v10 quad_perm:[2,3,0,1] row_mask:0xf bank_mask:0xf bound_ctrl:1
	v_pk_fma_f32 v[0:1], v[0:1], v[68:69], v[16:17] op_sel_hi:[1,0,1]
	v_pk_fma_f32 v[2:3], v[2:3], v[68:69], v[18:19] op_sel:[0,1,0] op_sel_hi:[1,1,1]
	v_add_f32_dpp v8, v8, v8 row_ror:4 row_mask:0xf bank_mask:0xf bound_ctrl:1
	v_add_f32_dpp v10, v10, v10 row_ror:4 row_mask:0xf bank_mask:0xf bound_ctrl:1
	v_pk_fma_f32 v[4:5], v[4:5], v[70:71], v[20:21] op_sel_hi:[1,0,1]
	v_add_f32_dpp v8, v8, v8 row_ror:8 row_mask:0xf bank_mask:0xf bound_ctrl:1
	v_mul_f32_e32 v8, s10, v8
	v_add_f32_dpp v99, v10, v10 row_ror:8 row_mask:0xf bank_mask:0x1 bound_ctrl:1
	v_pk_fma_f32 v[6:7], v[6:7], v[70:71], v[22:23] op_sel:[0,1,0] op_sel_hi:[1,1,1]
	v_mov_b32_dpp v9, v8 quad_perm:[1,0,3,2] row_mask:0xf bank_mask:0xf
	v_pk_fma_f32 v[0:1], v[8:9], v[72:73], v[0:1] op_sel_hi:[1,0,1] neg_lo:[1,0,0] neg_hi:[1,0,0]
	v_pk_fma_f32 v[2:3], v[8:9], v[72:73], v[2:3] op_sel:[0,1,0] op_sel_hi:[1,1,1] neg_lo:[1,0,0] neg_hi:[1,0,0]
	v_pk_fma_f32 v[4:5], v[8:9], v[74:75], v[4:5] op_sel_hi:[1,0,1] neg_lo:[1,0,0] neg_hi:[1,0,0]
	v_pk_fma_f32 v[6:7], v[8:9], v[74:75], v[6:7] op_sel:[0,1,0] op_sel_hi:[1,1,1] neg_lo:[1,0,0] neg_hi:[1,0,0]
	s_waitcnt lgkmcnt(0)
; #define VPKMUL(d, a, b) asm volatile("v_pk_mul_f32 %0, %1, %2" : "=v"(d) : "v"(a), "v"(b))
; __device__ __forceinline__ void scan_half(const Params& p, LAS unsigned char* lds, int pi, int rh, int pass) {
;     ...
;                 LOADREC(0, 0);
;                 float yp = 0.f, yk0 = 0.f, yk1 = 0.f, yk2 = 0.f, yk3 = 0.f;
;     ...
; #pragma unroll
;                 for (int s = 0; s < 32; ++s) {
;                     const int c = s & 1, pc = c ^ 1;
;                     const float si = __int_as_float(__builtin_amdgcn_readlane(__float_as_int(inv2), s));
;                     f32x2 px, py, t01, t23, t45, t67; float x;
;                     f32x2 vv2; vv2.x = Rv[c]; asm volatile("" : "+v"(vv2));
;                     if (s >= 1) {
;                         VPKMUL(px, P01, Rkk[c][0].xy); VPKMUL(py, P01, Rr[pc][0].xy); VPKFMA(px, P23, Rkk[c][0].zw, px); VPKFMA(py, P23, Rr[pc][0].zw, py);
;                         VPKFMA(px, P45, Rkk[c][1].xy, px); VPKFMA(py, P45, Rr[pc][1].xy, py); VPKFMA(px, P67, Rkk[c][1].zw, px); VPKFMA(py, P67, Rr[pc][1].zw, py);
;                         VADD(x, px.x, px.y); VADD(yp, py.x, py.y);
;                     } else {
;                         VPKMUL(px, P01, Rkk[c][0].xy); VPKFMA(px, P23, Rkk[c][0].zw, px); VPKFMA(px, P45, Rkk[c][1].xy, px); VPKFMA(px, P67, Rkk[c][1].zw, px);
;                         VADD(x, px.x, px.y);
;                     }
;                     asm volatile("" ::: "memory");
;                     if (s + 1 < 32) LOADREC((s + 1) & 1, s + 1);
;                     asm volatile("" ::: "memory");
;                     VPKMULBL(t01, vv2, Rkm[c][0].xy); VPKMULBL(t23, vv2, Rkm[c][0].zw);
;                     VDPP1(x); if (s >= 1) VDPP1(yp);
;                     VPKMULBL(t45, vv2, Rkm[c][1].xy); VPKMULBL(t67, vv2, Rkm[c][1].zw);
;                     VDPP2(x); if (s >= 1) VDPP2(yp);
;                     VPKFMA(P01, P01, Rw[c][0].xy, t01); VPKFMA(P23, P23, Rw[c][0].zw, t23);
;                     VDPP3(x); if (s >= 1) VDPP3(yp);
;                     VPKFMA(P45, P45, Rw[c][1].xy, t45); VPKFMA(P67, P67, Rw[c][1].zw, t67);
;                     if (s >= 1) { if (s - 1 < 8) YSHIFT(yk0); else if (s - 1 < 16) YSHIFT(yk1); else if (s - 1 < 24) YSHIFT(yk2); else YSHIFT(yk3); }
;                     x = x * si;
;                     f32x2 x2; x2.x = x; asm volatile("" : "+v"(x2));
	ds_read_b128 v[64:67], v35 offset:4080
	ds_read_b128 v[76:79], v35 offset:30192
	ds_read_b32 v94, v36 offset:1920
	ds_read_b32 v95, v38 offset:1920
	ds_read_b128 v[68:71], v35 offset:12784
	ds_read_b128 v[72:75], v35 offset:21488
	ds_read_b128 v[80:83], v35 offset:38896
	v_pk_mul_f32 v[8:9], v[0:1], v[48:49] op_sel_hi:[1,0]
	v_pk_mul_f32 v[10:11], v[0:1], v[84:85] op_sel_hi:[1,0]
	v_pk_fma_f32 v[8:9], v[2:3], v[48:49], v[8:9] op_sel:[0,1,0] op_sel_hi:[1,1,1]
	v_pk_fma_f32 v[10:11], v[2:3], v[84:85], v[10:11] op_sel:[0,1,0] op_sel_hi:[1,1,1]
	v_pk_fma_f32 v[8:9], v[4:5], v[50:51], v[8:9] op_sel_hi:[1,0,1]
	v_pk_fma_f32 v[10:11], v[4:5], v[86:87], v[10:11] op_sel_hi:[1,0,1]
	v_pk_fma_f32 v[8:9], v[6:7], v[50:51], v[8:9] op_sel:[0,1,0] op_sel_hi:[1,1,1]
	v_pk_fma_f32 v[10:11], v[6:7], v[86:87], v[10:11] op_sel:[0,1,0] op_sel_hi:[1,1,1]
	v_readlane_b32 s10, v34, 14
	v_pk_mul_f32 v[16:17], v[92:93], v[60:61] op_sel_hi:[1,0]
	v_pk_mul_f32 v[18:19], v[92:93], v[60:61] op_sel:[0,1] op_sel_hi:[1,1]
	v_add_f32_dpp v8, v9, v8 quad_perm:[1,0,3,2] row_mask:0xf bank_mask:0xf bound_ctrl:1
	v_add_f32_dpp v10, v11, v10 quad_perm:[1,0,3,2] row_mask:0xf bank_mask:0xf bound_ctrl:1
	v_pk_mul_f32 v[20:21], v[92:93], v[62:63] op_sel_hi:[1,0]
	v_pk_mul_f32 v[22:23], v[92:93], v[62:63] op_sel:[0,1] op_sel_hi:[1,1]
	v_add_f32_dpp v8, v8, v8 quad_perm:[2,3,0,1] row_mask:0xf bank_mask:0xf bound_ctrl:1
	v_add_f32_dpp v10, v10, v10 quad_perm:[2,3,0,1] row_mask:0xf bank_mask:0xf bound_ctrl:1
	v_pk_fma_f32 v[0:1], v[0:1], v[52:53], v[16:17] op_sel_hi:[1,0,1]
	v_pk_fma_f32 v[2:3], v[2:3], v[52:53], v[18:19] op_sel:[0,1,0] op_sel_hi:[1,1,1]
	v_add_f32_dpp v8, v8, v8 row_ror:4 row_mask:0xf bank_mask:0xf bound_ctrl:1
	v_add_f32_dpp v10, v10, v10 row_ror:4 row_mask:0xf bank_mask:0xf bound_ctrl:1
	v_pk_fma_f32 v[4:5], v[4:5], v[54:55], v[20:21] op_sel_hi:[1,0,1]
	v_add_f32_dpp v8, v8, v8 row_ror:8 row_mask:0xf bank_mask:0xf bound_ctrl:1
	v_mul_f32_e32 v8, s10, v8
	v_add_f32_dpp v99, v10, v10 row_ror:8 row_mask:0xf bank_mask:0x2 bound_ctrl:1
	v_pk_fma_f32 v[6:7], v[6:7], v[54:55], v[22:23] op_sel:[0,1,0] op_sel_hi:[1,1,1]
	v_mov_b32_dpp v9, v8 quad_perm:[1,0,3,2] row_mask:0xf bank_mask:0xf
	v_pk_fma_f32 v[0:1], v[8:9], v[56:57], v[0:1] op_sel_hi:[1,0,1] neg_lo:[1,0,0] neg_hi:[1,0,0]
	v_pk_fma_f32 v[2:3], v[8:9], v[56:57], v[2:3] op_sel:[0,1,0] op_sel_hi:[1,1,1] neg_lo:[1,0,0] neg_hi:[1,0,0]
	v_pk_fma_f32 v[4:5], v[8:9], v[58:59], v[4:5] op_sel_hi:[1,0,1] neg_lo:[1,0,0] neg_hi:[1,0,0]
	v_pk_fma_f32 v[6:7], v[8:9], v[58:59], v[6:7] op_sel:[0,1,0] op_sel_hi:[1,1,1] neg_lo:[1,0,0] neg_hi:[1,0,0]
	s_waitcnt lgkmcnt(0)
	ds_read_b128 v[48:51], v35 offset:4352
	ds_read_b128 v[60:63], v35 offset:30464
	ds_read_b32 v92, v36 offset:2048
	ds_read_b32 v93, v38 offset:2048
	ds_read_b128 v[52:55], v35 offset:13056
	ds_read_b128 v[56:59], v35 offset:21760
	ds_read_b128 v[84:87], v35 offset:39168
	v_pk_mul_f32 v[8:9], v[0:1], v[64:65] op_sel_hi:[1,0]
	v_pk_mul_f32 v[10:11], v[0:1], v[88:89] op_sel_hi:[1,0]
	v_pk_fma_f32 v[8:9], v[2:3], v[64:65], v[8:9] op_sel:[0,1,0] op_sel_hi:[1,1,1]
	v_pk_fma_f32 v[10:11], v[2:3], v[88:89], v[10:11] op_sel:[0,1,0] op_sel_hi:[1,1,1]
	v_pk_fma_f32 v[8:9], v[4:5], v[66:67], v[8:9] op_sel_hi:[1,0,1]
	v_pk_fma_f32 v[10:11], v[4:5], v[90:91], v[10:11] op_sel_hi:[1,0,1]
	v_pk_fma_f32 v[8:9], v[6:7], v[66:67], v[8:9] op_sel:[0,1,0] op_sel_hi:[1,1,1]
	v_pk_fma_f32 v[10:11], v[6:7], v[90:91], v[10:11] op_sel:[0,1,0] op_sel_hi:[1,1,1]
	v_readlane_b32 s10, v34, 15
	v_pk_mul_f32 v[16:17], v[94:95], v[76:77] op_sel_hi:[1,0]
	v_pk_mul_f32 v[18:19], v[94:95], v[76:77] op_sel:[0,1] op_sel_hi:[1,1]
	v_add_f32_dpp v8, v9, v8 quad_perm:[1,0,3,2] row_mask:0xf bank_mask:0xf bound_ctrl:1
	v_add_f32_dpp v10, v11, v10 quad_perm:[1,0,3,2] row_mask:0xf bank_mask:0xf bound_ctrl:1
	v_pk_mul_f32 v[20:21], v[94:95], v[78:79] op_sel_hi:[1,0]
	v_pk_mul_f32 v[22:23], v[94:95], v[78:79] op_sel:[0,1] op_sel_hi:[1,1]
	v_add_f32_dpp v8, v8, v8 quad_perm:[2,3,0,1] row_mask:0xf bank_mask:0xf bound_ctrl:1
	v_add_f32_dpp v10, v10, v10 quad_perm:[2,3,0,1] row_mask:0xf bank_mask:0xf bound_ctrl:1
	v_pk_fma_f32 v[0:1], v[0:1], v[68:69], v[16:17] op_sel_hi:[1,0,1]
	v_pk_fma_f32 v[2:3], v[2:3], v[68:69], v[18:19] op_sel:[0,1,0] op_sel_hi:[1,1,1]
	v_add_f32_dpp v8, v8, v8 row_ror:4 row_mask:0xf bank_mask:0xf bound_ctrl:1
	v_add_f32_dpp v10, v10, v10 row_ror:4 row_mask:0xf bank_mask:0xf bound_ctrl:1
	v_pk_fma_f32 v[4:5], v[4:5], v[70:71], v[20:21] op_sel_hi:[1,0,1]
	v_add_f32_dpp v8, v8, v8 row_ror:8 row_mask:0xf bank_mask:0xf bound_ctrl:1
	v_mul_f32_e32 v8, s10, v8
	v_add_f32_dpp v99, v10, v10 row_ror:8 row_mask:0xf bank_mask:0x4 bound_ctrl:1
	v_pk_fma_f32 v[6:7], v[6:7], v[70:71], v[22:23] op_sel:[0,1,0] op_sel_hi:[1,1,1]
	v_mov_b32_dpp v9, v8 quad_perm:[1,0,3,2] row_mask:0xf bank_mask:0xf
	v_pk_fma_f32 v[0:1], v[8:9], v[72:73], v[0:1] op_sel_hi:[1,0,1] neg_lo:[1,0,0] neg_hi:[1,0,0]
	v_pk_fma_f32 v[2:3], v[8:9], v[72:73], v[2:3] op_sel:[0,1,0] op_sel_hi:[1,1,1] neg_lo:[1,0,0] neg_hi:[1,0,0]
	v_pk_fma_f32 v[4:5], v[8:9], v[74:75], v[4:5] op_sel_hi:[1,0,1] neg_lo:[1,0,0] neg_hi:[1,0,0]
	v_pk_fma_f32 v[6:7], v[8:9], v[74:75], v[6:7] op_sel:[0,1,0] op_sel_hi:[1,1,1] neg_lo:[1,0,0] neg_hi:[1,0,0]
	s_waitcnt lgkmcnt(0)
; #define VPKMUL(d, a, b) asm volatile("v_pk_mul_f32 %0, %1, %2" : "=v"(d) : "v"(a), "v"(b))
; __device__ __forceinline__ void scan_half(const Params& p, LAS unsigned char* lds, int pi, int rh, int pass) {
;     ...
;                 LOADREC(0, 0);
;                 float yp = 0.f, yk0 = 0.f, yk1 = 0.f, yk2 = 0.f, yk3 = 0.f;
;     ...
; #pragma unroll
;                 for (int s = 0; s < 32; ++s) {
;                     const int c = s & 1, pc = c ^ 1;
;                     const float si = __int_as_float(__builtin_amdgcn_readlane(__float_as_int(inv2), s));
;                     f32x2 px, py, t01, t23, t45, t67; float x;
;                     f32x2 vv2; vv2.x = Rv[c]; asm volatile("" : "+v"(vv2));
;                     if (s >= 1) {
;                         VPKMUL(px, P01, Rkk[c][0].xy); VPKMUL(py, P01, Rr[pc][0].xy); VPKFMA(px, P23, Rkk[c][0].zw, px); VPKFMA(py, P23, Rr[pc][0].zw, py);
;                         VPKFMA(px, P45, Rkk[c][1].xy, px); VPKFMA(py, P45, Rr[pc][1].xy, py); VPKFMA(px, P67, Rkk[c][1].zw, px); VPKFMA(py, P67, Rr[pc][1].zw, py);
;                         VADD(x, px.x, px.y); VADD(yp, py.x, py.y);
;                     } else {
;                         VPKMUL(px, P01, Rkk[c][0].xy); VPKFMA(px, P23, Rkk[c][0].zw, px); VPKFMA(px, P45, Rkk[c][1].xy, px); VPKFMA(px, P67, Rkk[c][1].zw, px);
;                         VADD(x, px.x, px.y);
;                     }
;                     asm volatile("" ::: "memory");
;                     if (s + 1 < 32) LOADREC((s + 1) & 1, s + 1);
;                     asm volatile("" ::: "memory");
;                     VPKMULBL(t01, vv2, Rkm[c][0].xy); VPKMULBL(t23, vv2, Rkm[c][0].zw);
;                     VDPP1(x); if (s >= 1) VDPP1(yp);
;                     VPKMULBL(t45, vv2, Rkm[c][1].xy); VPKMULBL(t67, vv2, Rkm[c][1].zw);
;                     VDPP2(x); if (s >= 1) VDPP2(yp);
;                     VPKFMA(P01, P01, Rw[c][0].xy, t01); VPKFMA(P23, P23, Rw[c][0].zw, t23);
;                     VDPP3(x); if (s >= 1) VDPP3(yp);
;                     VPKFMA(P45, P45, Rw[c][1].xy, t45); VPKFMA(P67, P67, Rw[c][1].zw, t67);
;                     if (s >= 1) { if (s - 1 < 8) YSHIFT(yk0); else if (s - 1 < 16) YSHIFT(yk1); else if (s - 1 < 24) YSHIFT(yk2); else YSHIFT(yk3); }
;                     x = x * si;
;                     f32x2 x2; x2.x = x; asm volatile("" : "+v"(x2));
	ds_read_b128 v[64:67], v35 offset:4624
	ds_read_b128 v[76:79], v35 offset:30736
	ds_read_b32 v94, v36 offset:2176
	ds_read_b32 v95, v38 offset:2176
	ds_read_b128 v[68:71], v35 offset:13328
	ds_read_b128 v[72:75], v35 offset:22032
	ds_read_b128 v[88:91], v35 offset:39440
	v_pk_mul_f32 v[8:9], v[0:1], v[48:49] op_sel_hi:[1,0]
	v_pk_mul_f32 v[10:11], v[0:1], v[80:81] op_sel_hi:[1,0]
	v_pk_fma_f32 v[8:9], v[2:3], v[48:49], v[8:9] op_sel:[0,1,0] op_sel_hi:[1,1,1]
	v_pk_fma_f32 v[10:11], v[2:3], v[80:81], v[10:11] op_sel:[0,1,0] op_sel_hi:[1,1,1]
	v_pk_fma_f32 v[8:9], v[4:5], v[50:51], v[8:9] op_sel_hi:[1,0,1]
	v_pk_fma_f32 v[10:11], v[4:5], v[82:83], v[10:11] op_sel_hi:[1,0,1]
	v_pk_fma_f32 v[8:9], v[6:7], v[50:51], v[8:9] op_sel:[0,1,0] op_sel_hi:[1,1,1]
	v_pk_fma_f32 v[10:11], v[6:7], v[82:83], v[10:11] op_sel:[0,1,0] op_sel_hi:[1,1,1]
	v_readlane_b32 s10, v34, 16
	v_pk_mul_f32 v[16:17], v[92:93], v[60:61] op_sel_hi:[1,0]
	v_pk_mul_f32 v[18:19], v[92:93], v[60:61] op_sel:[0,1] op_sel_hi:[1,1]
	v_add_f32_dpp v8, v9, v8 quad_perm:[1,0,3,2] row_mask:0xf bank_mask:0xf bound_ctrl:1
	v_add_f32_dpp v10, v11, v10 quad_perm:[1,0,3,2] row_mask:0xf bank_mask:0xf bound_ctrl:1
	v_pk_mul_f32 v[20:21], v[92:93], v[62:63] op_sel_hi:[1,0]
	v_pk_mul_f32 v[22:23], v[92:93], v[62:63] op_sel:[0,1] op_sel_hi:[1,1]
	v_add_f32_dpp v8, v8, v8 quad_perm:[2,3,0,1] row_mask:0xf bank_mask:0xf bound_ctrl:1
	v_add_f32_dpp v10, v10, v10 quad_perm:[2,3,0,1] row_mask:0xf bank_mask:0xf bound_ctrl:1
	v_pk_fma_f32 v[0:1], v[0:1], v[52:53], v[16:17] op_sel_hi:[1,0,1]
	v_pk_fma_f32 v[2:3], v[2:3], v[52:53], v[18:19] op_sel:[0,1,0] op_sel_hi:[1,1,1]
	v_add_f32_dpp v8, v8, v8 row_ror:4 row_mask:0xf bank_mask:0xf bound_ctrl:1
	v_add_f32_dpp v10, v10, v10 row_ror:4 row_mask:0xf bank_mask:0xf bound_ctrl:1
	v_pk_fma_f32 v[4:5], v[4:5], v[54:55], v[20:21] op_sel_hi:[1,0,1]
	v_add_f32_dpp v8, v8, v8 row_ror:8 row_mask:0xf bank_mask:0xf bound_ctrl:1
	v_mul_f32_e32 v8, s10, v8
	v_add_f32_dpp v99, v10, v10 row_ror:8 row_mask:0xf bank_mask:0x8 bound_ctrl:1
	v_pk_fma_f32 v[6:7], v[6:7], v[54:55], v[22:23] op_sel:[0,1,0] op_sel_hi:[1,1,1]
	v_mov_b32_dpp v9, v8 quad_perm:[1,0,3,2] row_mask:0xf bank_mask:0xf
	v_pk_fma_f32 v[0:1], v[8:9], v[56:57], v[0:1] op_sel_hi:[1,0,1] neg_lo:[1,0,0] neg_hi:[1,0,0]
	v_pk_fma_f32 v[2:3], v[8:9], v[56:57], v[2:3] op_sel:[0,1,0] op_sel_hi:[1,1,1] neg_lo:[1,0,0] neg_hi:[1,0,0]
	v_pk_fma_f32 v[4:5], v[8:9], v[58:59], v[4:5] op_sel_hi:[1,0,1] neg_lo:[1,0,0] neg_hi:[1,0,0]
	v_pk_fma_f32 v[6:7], v[8:9], v[58:59], v[6:7] op_sel:[0,1,0] op_sel_hi:[1,1,1] neg_lo:[1,0,0] neg_hi:[1,0,0]
	s_waitcnt lgkmcnt(0)
	ds_read_b128 v[48:51], v35 offset:4896
	ds_read_b128 v[60:63], v35 offset:31008
	ds_read_b32 v92, v36 offset:2304
	ds_read_b32 v93, v38 offset:2304
	ds_read_b128 v[52:55], v35 offset:13600
	ds_read_b128 v[56:59], v35 offset:22304
	ds_read_b128 v[80:83], v35 offset:39712
	v_pk_mul_f32 v[8:9], v[0:1], v[64:65] op_sel_hi:[1,0]
	v_pk_mul_f32 v[10:11], v[0:1], v[84:85] op_sel_hi:[1,0]
	v_pk_fma_f32 v[8:9], v[2:3], v[64:65], v[8:9] op_sel:[0,1,0] op_sel_hi:[1,1,1]
	v_pk_fma_f32 v[10:11], v[2:3], v[84:85], v[10:11] op_sel:[0,1,0] op_sel_hi:[1,1,1]
	v_pk_fma_f32 v[8:9], v[4:5], v[66:67], v[8:9] op_sel_hi:[1,0,1]
	v_pk_fma_f32 v[10:11], v[4:5], v[86:87], v[10:11] op_sel_hi:[1,0,1]
	v_pk_fma_f32 v[8:9], v[6:7], v[66:67], v[8:9] op_sel:[0,1,0] op_sel_hi:[1,1,1]
	v_pk_fma_f32 v[10:11], v[6:7], v[86:87], v[10:11] op_sel:[0,1,0] op_sel_hi:[1,1,1]
	v_readlane_b32 s10, v34, 17
	v_pk_mul_f32 v[16:17], v[94:95], v[76:77] op_sel_hi:[1,0]
	v_pk_mul_f32 v[18:19], v[94:95], v[76:77] op_sel:[0,1] op_sel_hi:[1,1]
	v_add_f32_dpp v8, v9, v8 quad_perm:[1,0,3,2] row_mask:0xf bank_mask:0xf bound_ctrl:1
	v_add_f32_dpp v10, v11, v10 quad_perm:[1,0,3,2] row_mask:0xf bank_mask:0xf bound_ctrl:1
	v_pk_mul_f32 v[20:21], v[94:95], v[78:79] op_sel_hi:[1,0]
	v_pk_mul_f32 v[22:23], v[94:95], v[78:79] op_sel:[0,1] op_sel_hi:[1,1]
	v_add_f32_dpp v8, v8, v8 quad_perm:[2,3,0,1] row_mask:0xf bank_mask:0xf bound_ctrl:1
	v_add_f32_dpp v10, v10, v10 quad_perm:[2,3,0,1] row_mask:0xf bank_mask:0xf bound_ctrl:1
	v_pk_fma_f32 v[0:1], v[0:1], v[68:69], v[16:17] op_sel_hi:[1,0,1]
	v_pk_fma_f32 v[2:3], v[2:3], v[68:69], v[18:19] op_sel:[0,1,0] op_sel_hi:[1,1,1]
	v_add_f32_dpp v8, v8, v8 row_ror:4 row_mask:0xf bank_mask:0xf bound_ctrl:1
	v_add_f32_dpp v10, v10, v10 row_ror:4 row_mask:0xf bank_mask:0xf bound_ctrl:1
	v_pk_fma_f32 v[4:5], v[4:5], v[70:71], v[20:21] op_sel_hi:[1,0,1]
	v_add_f32_dpp v8, v8, v8 row_ror:8 row_mask:0xf bank_mask:0xf bound_ctrl:1
	v_mul_f32_e32 v8, s10, v8
	v_add_f32_dpp v100, v10, v10 row_ror:8 row_mask:0xf bank_mask:0x1 bound_ctrl:1
	v_pk_fma_f32 v[6:7], v[6:7], v[70:71], v[22:23] op_sel:[0,1,0] op_sel_hi:[1,1,1]
	v_mov_b32_dpp v9, v8 quad_perm:[1,0,3,2] row_mask:0xf bank_mask:0xf
	v_pk_fma_f32 v[0:1], v[8:9], v[72:73], v[0:1] op_sel_hi:[1,0,1] neg_lo:[1,0,0] neg_hi:[1,0,0]
	v_pk_fma_f32 v[2:3], v[8:9], v[72:73], v[2:3] op_sel:[0,1,0] op_sel_hi:[1,1,1] neg_lo:[1,0,0] neg_hi:[1,0,0]
	v_pk_fma_f32 v[4:5], v[8:9], v[74:75], v[4:5] op_sel_hi:[1,0,1] neg_lo:[1,0,0] neg_hi:[1,0,0]
	v_pk_fma_f32 v[6:7], v[8:9], v[74:75], v[6:7] op_sel:[0,1,0] op_sel_hi:[1,1,1] neg_lo:[1,0,0] neg_hi:[1,0,0]
	s_waitcnt lgkmcnt(0)
; #define VPKMUL(d, a, b) asm volatile("v_pk_mul_f32 %0, %1, %2" : "=v"(d) : "v"(a), "v"(b))
; __device__ __forceinline__ void scan_half(const Params& p, LAS unsigned char* lds, int pi, int rh, int pass) {
;     ...
;                 LOADREC(0, 0);
;                 float yp = 0.f, yk0 = 0.f, yk1 = 0.f, yk2 = 0.f, yk3 = 0.f;
;     ...
; #pragma unroll
;                 for (int s = 0; s < 32; ++s) {
;                     const int c = s & 1, pc = c ^ 1;
;                     const float si = __int_as_float(__builtin_amdgcn_readlane(__float_as_int(inv2), s));
;                     f32x2 px, py, t01, t23, t45, t67; float x;
;                     f32x2 vv2; vv2.x = Rv[c]; asm volatile("" : "+v"(vv2));
;                     if (s >= 1) {
;                         VPKMUL(px, P01, Rkk[c][0].xy); VPKMUL(py, P01, Rr[pc][0].xy); VPKFMA(px, P23, Rkk[c][0].zw, px); VPKFMA(py, P23, Rr[pc][0].zw, py);
;                         VPKFMA(px, P45, Rkk[c][1].xy, px); VPKFMA(py, P45, Rr[pc][1].xy, py); VPKFMA(px, P67, Rkk[c][1].zw, px); VPKFMA(py, P67, Rr[pc][1].zw, py);
;                         VADD(x, px.x, px.y); VADD(yp, py.x, py.y);
;                     } else {
;                         VPKMUL(px, P01, Rkk[c][0].xy); VPKFMA(px, P23, Rkk[c][0].zw, px); VPKFMA(px, P45, Rkk[c][1].xy, px); VPKFMA(px, P67, Rkk[c][1].zw, px);
;                         VADD(x, px.x, px.y);
;                     }
;                     asm volatile("" ::: "memory");
;                     if (s + 1 < 32) LOADREC((s + 1) & 1, s + 1);
;                     asm volatile("" ::: "memory");
;                     VPKMULBL(t01, vv2, Rkm[c][0].xy); VPKMULBL(t23, vv2, Rkm[c][0].zw);
;                     VDPP1(x); if (s >= 1) VDPP1(yp);
;                     VPKMULBL(t45, vv2, Rkm[c][1].xy); VPKMULBL(t67, vv2, Rkm[c][1].zw);
;                     VDPP2(x); if (s >= 1) VDPP2(yp);
;                     VPKFMA(P01, P01, Rw[c][0].xy, t01); VPKFMA(P23, P23, Rw[c][0].zw, t23);
;                     VDPP3(x); if (s >= 1) VDPP3(yp);
;                     VPKFMA(P45, P45, Rw[c][1].xy, t45); VPKFMA(P67, P67, Rw[c][1].zw, t67);
;                     if (s >= 1) { if (s - 1 < 8) YSHIFT(yk0); else if (s - 1 < 16) YSHIFT(yk1); else if (s - 1 < 24) YSHIFT(yk2); else YSHIFT(yk3); }
;                     x = x * si;
;                     f32x2 x2; x2.x = x; asm volatile("" : "+v"(x2));
	ds_read_b128 v[64:67], v35 offset:5168
	ds_read_b128 v[76:79], v35 offset:31280
	ds_read_b32 v94, v36 offset:2432
	ds_read_b32 v95, v38 offset:2432
	ds_read_b128 v[68:71], v35 offset:13872
	ds_read_b128 v[72:75], v35 offset:22576
	ds_read_b128 v[84:87], v35 offset:39984
	v_pk_mul_f32 v[8:9], v[0:1], v[48:49] op_sel_hi:[1,0]
	v_pk_mul_f32 v[10:11], v[0:1], v[88:89] op_sel_hi:[1,0]
	v_pk_fma_f32 v[8:9], v[2:3], v[48:49], v[8:9] op_sel:[0,1,0] op_sel_hi:[1,1,1]
	v_pk_fma_f32 v[10:11], v[2:3], v[88:89], v[10:11] op_sel:[0,1,0] op_sel_hi:[1,1,1]
	v_pk_fma_f32 v[8:9], v[4:5], v[50:51], v[8:9] op_sel_hi:[1,0,1]
	v_pk_fma_f32 v[10:11], v[4:5], v[90:91], v[10:11] op_sel_hi:[1,0,1]
	v_pk_fma_f32 v[8:9], v[6:7], v[50:51], v[8:9] op_sel:[0,1,0] op_sel_hi:[1,1,1]
	v_pk_fma_f32 v[10:11], v[6:7], v[90:91], v[10:11] op_sel:[0,1,0] op_sel_hi:[1,1,1]
	v_readlane_b32 s10, v34, 18
	v_pk_mul_f32 v[16:17], v[92:93], v[60:61] op_sel_hi:[1,0]
	v_pk_mul_f32 v[18:19], v[92:93], v[60:61] op_sel:[0,1] op_sel_hi:[1,1]
	v_add_f32_dpp v8, v9, v8 quad_perm:[1,0,3,2] row_mask:0xf bank_mask:0xf bound_ctrl:1
	v_add_f32_dpp v10, v11, v10 quad_perm:[1,0,3,2] row_mask:0xf bank_mask:0xf bound_ctrl:1
	v_pk_mul_f32 v[20:21], v[92:93], v[62:63] op_sel_hi:[1,0]
	v_pk_mul_f32 v[22:23], v[92:93], v[62:63] op_sel:[0,1] op_sel_hi:[1,1]
	v_add_f32_dpp v8, v8, v8 quad_perm:[2,3,0,1] row_mask:0xf bank_mask:0xf bound_ctrl:1
	v_add_f32_dpp v10, v10, v10 quad_perm:[2,3,0,1] row_mask:0xf bank_mask:0xf bound_ctrl:1
	v_pk_fma_f32 v[0:1], v[0:1], v[52:53], v[16:17] op_sel_hi:[1,0,1]
	v_pk_fma_f32 v[2:3], v[2:3], v[52:53], v[18:19] op_sel:[0,1,0] op_sel_hi:[1,1,1]
	v_add_f32_dpp v8, v8, v8 row_ror:4 row_mask:0xf bank_mask:0xf bound_ctrl:1
	v_add_f32_dpp v10, v10, v10 row_ror:4 row_mask:0xf bank_mask:0xf bound_ctrl:1
	v_pk_fma_f32 v[4:5], v[4:5], v[54:55], v[20:21] op_sel_hi:[1,0,1]
	v_add_f32_dpp v8, v8, v8 row_ror:8 row_mask:0xf bank_mask:0xf bound_ctrl:1
	v_mul_f32_e32 v8, s10, v8
	v_add_f32_dpp v100, v10, v10 row_ror:8 row_mask:0xf bank_mask:0x2 bound_ctrl:1
	v_pk_fma_f32 v[6:7], v[6:7], v[54:55], v[22:23] op_sel:[0,1,0] op_sel_hi:[1,1,1]
	v_mov_b32_dpp v9, v8 quad_perm:[1,0,3,2] row_mask:0xf bank_mask:0xf
	v_pk_fma_f32 v[0:1], v[8:9], v[56:57], v[0:1] op_sel_hi:[1,0,1] neg_lo:[1,0,0] neg_hi:[1,0,0]
	v_pk_fma_f32 v[2:3], v[8:9], v[56:57], v[2:3] op_sel:[0,1,0] op_sel_hi:[1,1,1] neg_lo:[1,0,0] neg_hi:[1,0,0]
	v_pk_fma_f32 v[4:5], v[8:9], v[58:59], v[4:5] op_sel_hi:[1,0,1] neg_lo:[1,0,0] neg_hi:[1,0,0]
	v_pk_fma_f32 v[6:7], v[8:9], v[58:59], v[6:7] op_sel:[0,1,0] op_sel_hi:[1,1,1] neg_lo:[1,0,0] neg_hi:[1,0,0]
	s_waitcnt lgkmcnt(0)
	ds_read_b128 v[48:51], v35 offset:5440
	ds_read_b128 v[60:63], v35 offset:31552
	ds_read_b32 v92, v36 offset:2560
	ds_read_b32 v93, v38 offset:2560
	ds_read_b128 v[52:55], v35 offset:14144
	ds_read_b128 v[56:59], v35 offset:22848
	ds_read_b128 v[88:91], v35 offset:40256
	v_pk_mul_f32 v[8:9], v[0:1], v[64:65] op_sel_hi:[1,0]
	v_pk_mul_f32 v[10:11], v[0:1], v[80:81] op_sel_hi:[1,0]
	v_pk_fma_f32 v[8:9], v[2:3], v[64:65], v[8:9] op_sel:[0,1,0] op_sel_hi:[1,1,1]
	v_pk_fma_f32 v[10:11], v[2:3], v[80:81], v[10:11] op_sel:[0,1,0] op_sel_hi:[1,1,1]
	v_pk_fma_f32 v[8:9], v[4:5], v[66:67], v[8:9] op_sel_hi:[1,0,1]
	v_pk_fma_f32 v[10:11], v[4:5], v[82:83], v[10:11] op_sel_hi:[1,0,1]
	v_pk_fma_f32 v[8:9], v[6:7], v[66:67], v[8:9] op_sel:[0,1,0] op_sel_hi:[1,1,1]
	v_pk_fma_f32 v[10:11], v[6:7], v[82:83], v[10:11] op_sel:[0,1,0] op_sel_hi:[1,1,1]
	v_readlane_b32 s10, v34, 19
	v_pk_mul_f32 v[16:17], v[94:95], v[76:77] op_sel_hi:[1,0]
	v_pk_mul_f32 v[18:19], v[94:95], v[76:77] op_sel:[0,1] op_sel_hi:[1,1]
	v_add_f32_dpp v8, v9, v8 quad_perm:[1,0,3,2] row_mask:0xf bank_mask:0xf bound_ctrl:1
	v_add_f32_dpp v10, v11, v10 quad_perm:[1,0,3,2] row_mask:0xf bank_mask:0xf bound_ctrl:1
	v_pk_mul_f32 v[20:21], v[94:95], v[78:79] op_sel_hi:[1,0]
	v_pk_mul_f32 v[22:23], v[94:95], v[78:79] op_sel:[0,1] op_sel_hi:[1,1]
	v_add_f32_dpp v8, v8, v8 quad_perm:[2,3,0,1] row_mask:0xf bank_mask:0xf bound_ctrl:1
	v_add_f32_dpp v10, v10, v10 quad_perm:[2,3,0,1] row_mask:0xf bank_mask:0xf bound_ctrl:1
	v_pk_fma_f32 v[0:1], v[0:1], v[68:69], v[16:17] op_sel_hi:[1,0,1]
	v_pk_fma_f32 v[2:3], v[2:3], v[68:69], v[18:19] op_sel:[0,1,0] op_sel_hi:[1,1,1]
	v_add_f32_dpp v8, v8, v8 row_ror:4 row_mask:0xf bank_mask:0xf bound_ctrl:1
	v_add_f32_dpp v10, v10, v10 row_ror:4 row_mask:0xf bank_mask:0xf bound_ctrl:1
	v_pk_fma_f32 v[4:5], v[4:5], v[70:71], v[20:21] op_sel_hi:[1,0,1]
	v_add_f32_dpp v8, v8, v8 row_ror:8 row_mask:0xf bank_mask:0xf bound_ctrl:1
	v_mul_f32_e32 v8, s10, v8
	v_add_f32_dpp v100, v10, v10 row_ror:8 row_mask:0xf bank_mask:0x4 bound_ctrl:1
	v_pk_fma_f32 v[6:7], v[6:7], v[70:71], v[22:23] op_sel:[0,1,0] op_sel_hi:[1,1,1]
	v_mov_b32_dpp v9, v8 quad_perm:[1,0,3,2] row_mask:0xf bank_mask:0xf
	v_pk_fma_f32 v[0:1], v[8:9], v[72:73], v[0:1] op_sel_hi:[1,0,1] neg_lo:[1,0,0] neg_hi:[1,0,0]
	v_pk_fma_f32 v[2:3], v[8:9], v[72:73], v[2:3] op_sel:[0,1,0] op_sel_hi:[1,1,1] neg_lo:[1,0,0] neg_hi:[1,0,0]
	v_pk_fma_f32 v[4:5], v[8:9], v[74:75], v[4:5] op_sel_hi:[1,0,1] neg_lo:[1,0,0] neg_hi:[1,0,0]
	v_pk_fma_f32 v[6:7], v[8:9], v[74:75], v[6:7] op_sel:[0,1,0] op_sel_hi:[1,1,1] neg_lo:[1,0,0] neg_hi:[1,0,0]
	s_waitcnt lgkmcnt(0)
; #define VPKMUL(d, a, b) asm volatile("v_pk_mul_f32 %0, %1, %2" : "=v"(d) : "v"(a), "v"(b))
; __device__ __forceinline__ void scan_half(const Params& p, LAS unsigned char* lds, int pi, int rh, int pass) {
;     ...
;                 LOADREC(0, 0);
;                 float yp = 0.f, yk0 = 0.f, yk1 = 0.f, yk2 = 0.f, yk3 = 0.f;
;     ...
; #pragma unroll
;                 for (int s = 0; s < 32; ++s) {
;                     const int c = s & 1, pc = c ^ 1;
;                     const float si = __int_as_float(__builtin_amdgcn_readlane(__float_as_int(inv2), s));
;                     f32x2 px, py, t01, t23, t45, t67; float x;
;                     f32x2 vv2; vv2.x = Rv[c]; asm volatile("" : "+v"(vv2));
;                     if (s >= 1) {
;                         VPKMUL(px, P01, Rkk[c][0].xy); VPKMUL(py, P01, Rr[pc][0].xy); VPKFMA(px, P23, Rkk[c][0].zw, px); VPKFMA(py, P23, Rr[pc][0].zw, py);
;                         VPKFMA(px, P45, Rkk[c][1].xy, px); VPKFMA(py, P45, Rr[pc][1].xy, py); VPKFMA(px, P67, Rkk[c][1].zw, px); VPKFMA(py, P67, Rr[pc][1].zw, py);
;                         VADD(x, px.x, px.y); VADD(yp, py.x, py.y);
;                     } else {
;                         VPKMUL(px, P01, Rkk[c][0].xy); VPKFMA(px, P23, Rkk[c][0].zw, px); VPKFMA(px, P45, Rkk[c][1].xy, px); VPKFMA(px, P67, Rkk[c][1].zw, px);
;                         VADD(x, px.x, px.y);
;                     }
;                     asm volatile("" ::: "memory");
;                     if (s + 1 < 32) LOADREC((s + 1) & 1, s + 1);
;                     asm volatile("" ::: "memory");
;                     VPKMULBL(t01, vv2, Rkm[c][0].xy); VPKMULBL(t23, vv2, Rkm[c][0].zw);
;                     VDPP1(x); if (s >= 1) VDPP1(yp);
;                     VPKMULBL(t45, vv2, Rkm[c][1].xy); VPKMULBL(t67, vv2, Rkm[c][1].zw);
;                     VDPP2(x); if (s >= 1) VDPP2(yp);
;                     VPKFMA(P01, P01, Rw[c][0].xy, t01); VPKFMA(P23, P23, Rw[c][0].zw, t23);
;                     VDPP3(x); if (s >= 1) VDPP3(yp);
;                     VPKFMA(P45, P45, Rw[c][1].xy, t45); VPKFMA(P67, P67, Rw[c][1].zw, t67);
;                     if (s >= 1) { if (s - 1 < 8) YSHIFT(yk0); else if (s - 1 < 16) YSHIFT(yk1); else if (s - 1 < 24) YSHIFT(yk2); else YSHIFT(yk3); }
;                     x = x * si;
;                     f32x2 x2; x2.x = x; asm volatile("" : "+v"(x2));
	ds_read_b128 v[64:67], v35 offset:5712
	ds_read_b128 v[76:79], v35 offset:31824
	ds_read_b32 v94, v36 offset:2688
	ds_read_b32 v95, v38 offset:2688
	ds_read_b128 v[68:71], v35 offset:14416
	ds_read_b128 v[72:75], v35 offset:23120
	ds_read_b128 v[80:83], v35 offset:40528
	v_pk_mul_f32 v[8:9], v[0:1], v[48:49] op_sel_hi:[1,0]
	v_pk_mul_f32 v[10:11], v[0:1], v[84:85] op_sel_hi:[1,0]
	v_pk_fma_f32 v[8:9], v[2:3], v[48:49], v[8:9] op_sel:[0,1,0] op_sel_hi:[1,1,1]
	v_pk_fma_f32 v[10:11], v[2:3], v[84:85], v[10:11] op_sel:[0,1,0] op_sel_hi:[1,1,1]
	v_pk_fma_f32 v[8:9], v[4:5], v[50:51], v[8:9] op_sel_hi:[1,0,1]
	v_pk_fma_f32 v[10:11], v[4:5], v[86:87], v[10:11] op_sel_hi:[1,0,1]
	v_pk_fma_f32 v[8:9], v[6:7], v[50:51], v[8:9] op_sel:[0,1,0] op_sel_hi:[1,1,1]
	v_pk_fma_f32 v[10:11], v[6:7], v[86:87], v[10:11] op_sel:[0,1,0] op_sel_hi:[1,1,1]
	v_readlane_b32 s10, v34, 20
	v_pk_mul_f32 v[16:17], v[92:93], v[60:61] op_sel_hi:[1,0]
	v_pk_mul_f32 v[18:19], v[92:93], v[60:61] op_sel:[0,1] op_sel_hi:[1,1]
	v_add_f32_dpp v8, v9, v8 quad_perm:[1,0,3,2] row_mask:0xf bank_mask:0xf bound_ctrl:1
	v_add_f32_dpp v10, v11, v10 quad_perm:[1,0,3,2] row_mask:0xf bank_mask:0xf bound_ctrl:1
	v_pk_mul_f32 v[20:21], v[92:93], v[62:63] op_sel_hi:[1,0]
	v_pk_mul_f32 v[22:23], v[92:93], v[62:63] op_sel:[0,1] op_sel_hi:[1,1]
	v_add_f32_dpp v8, v8, v8 quad_perm:[2,3,0,1] row_mask:0xf bank_mask:0xf bound_ctrl:1
	v_add_f32_dpp v10, v10, v10 quad_perm:[2,3,0,1] row_mask:0xf bank_mask:0xf bound_ctrl:1
	v_pk_fma_f32 v[0:1], v[0:1], v[52:53], v[16:17] op_sel_hi:[1,0,1]
	v_pk_fma_f32 v[2:3], v[2:3], v[52:53], v[18:19] op_sel:[0,1,0] op_sel_hi:[1,1,1]
	v_add_f32_dpp v8, v8, v8 row_ror:4 row_mask:0xf bank_mask:0xf bound_ctrl:1
	v_add_f32_dpp v10, v10, v10 row_ror:4 row_mask:0xf bank_mask:0xf bound_ctrl:1
	v_pk_fma_f32 v[4:5], v[4:5], v[54:55], v[20:21] op_sel_hi:[1,0,1]
	v_add_f32_dpp v8, v8, v8 row_ror:8 row_mask:0xf bank_mask:0xf bound_ctrl:1
	v_mul_f32_e32 v8, s10, v8
	v_add_f32_dpp v100, v10, v10 row_ror:8 row_mask:0xf bank_mask:0x8 bound_ctrl:1
	v_pk_fma_f32 v[6:7], v[6:7], v[54:55], v[22:23] op_sel:[0,1,0] op_sel_hi:[1,1,1]
	v_mov_b32_dpp v9, v8 quad_perm:[1,0,3,2] row_mask:0xf bank_mask:0xf
	v_pk_fma_f32 v[0:1], v[8:9], v[56:57], v[0:1] op_sel_hi:[1,0,1] neg_lo:[1,0,0] neg_hi:[1,0,0]
	v_pk_fma_f32 v[2:3], v[8:9], v[56:57], v[2:3] op_sel:[0,1,0] op_sel_hi:[1,1,1] neg_lo:[1,0,0] neg_hi:[1,0,0]
	v_pk_fma_f32 v[4:5], v[8:9], v[58:59], v[4:5] op_sel_hi:[1,0,1] neg_lo:[1,0,0] neg_hi:[1,0,0]
	v_pk_fma_f32 v[6:7], v[8:9], v[58:59], v[6:7] op_sel:[0,1,0] op_sel_hi:[1,1,1] neg_lo:[1,0,0] neg_hi:[1,0,0]
	s_waitcnt lgkmcnt(0)
	ds_read_b128 v[48:51], v35 offset:5984
	ds_read_b128 v[60:63], v35 offset:32096
	ds_read_b32 v92, v36 offset:2816
	ds_read_b32 v93, v38 offset:2816
	ds_read_b128 v[52:55], v35 offset:14688
	ds_read_b128 v[56:59], v35 offset:23392
	ds_read_b128 v[84:87], v35 offset:40800
	v_pk_mul_f32 v[8:9], v[0:1], v[64:65] op_sel_hi:[1,0]
	v_pk_mul_f32 v[10:11], v[0:1], v[88:89] op_sel_hi:[1,0]
	v_pk_fma_f32 v[8:9], v[2:3], v[64:65], v[8:9] op_sel:[0,1,0] op_sel_hi:[1,1,1]
	v_pk_fma_f32 v[10:11], v[2:3], v[88:89], v[10:11] op_sel:[0,1,0] op_sel_hi:[1,1,1]
	v_pk_fma_f32 v[8:9], v[4:5], v[66:67], v[8:9] op_sel_hi:[1,0,1]
	v_pk_fma_f32 v[10:11], v[4:5], v[90:91], v[10:11] op_sel_hi:[1,0,1]
	v_pk_fma_f32 v[8:9], v[6:7], v[66:67], v[8:9] op_sel:[0,1,0] op_sel_hi:[1,1,1]
	v_pk_fma_f32 v[10:11], v[6:7], v[90:91], v[10:11] op_sel:[0,1,0] op_sel_hi:[1,1,1]
	v_readlane_b32 s10, v34, 21
	v_pk_mul_f32 v[16:17], v[94:95], v[76:77] op_sel_hi:[1,0]
	v_pk_mul_f32 v[18:19], v[94:95], v[76:77] op_sel:[0,1] op_sel_hi:[1,1]
	v_add_f32_dpp v8, v9, v8 quad_perm:[1,0,3,2] row_mask:0xf bank_mask:0xf bound_ctrl:1
	v_add_f32_dpp v10, v11, v10 quad_perm:[1,0,3,2] row_mask:0xf bank_mask:0xf bound_ctrl:1
	v_pk_mul_f32 v[20:21], v[94:95], v[78:79] op_sel_hi:[1,0]
	v_pk_mul_f32 v[22:23], v[94:95], v[78:79] op_sel:[0,1] op_sel_hi:[1,1]
	v_add_f32_dpp v8, v8, v8 quad_perm:[2,3,0,1] row_mask:0xf bank_mask:0xf bound_ctrl:1
	v_add_f32_dpp v10, v10, v10 quad_perm:[2,3,0,1] row_mask:0xf bank_mask:0xf bound_ctrl:1
	v_pk_fma_f32 v[0:1], v[0:1], v[68:69], v[16:17] op_sel_hi:[1,0,1]
	v_pk_fma_f32 v[2:3], v[2:3], v[68:69], v[18:19] op_sel:[0,1,0] op_sel_hi:[1,1,1]
	v_add_f32_dpp v8, v8, v8 row_ror:4 row_mask:0xf bank_mask:0xf bound_ctrl:1
	v_add_f32_dpp v10, v10, v10 row_ror:4 row_mask:0xf bank_mask:0xf bound_ctrl:1
	v_pk_fma_f32 v[4:5], v[4:5], v[70:71], v[20:21] op_sel_hi:[1,0,1]
	v_add_f32_dpp v8, v8, v8 row_ror:8 row_mask:0xf bank_mask:0xf bound_ctrl:1
	v_mul_f32_e32 v8, s10, v8
	v_add_f32_dpp v101, v10, v10 row_ror:8 row_mask:0xf bank_mask:0x1 bound_ctrl:1
	v_pk_fma_f32 v[6:7], v[6:7], v[70:71], v[22:23] op_sel:[0,1,0] op_sel_hi:[1,1,1]
	v_mov_b32_dpp v9, v8 quad_perm:[1,0,3,2] row_mask:0xf bank_mask:0xf
	v_pk_fma_f32 v[0:1], v[8:9], v[72:73], v[0:1] op_sel_hi:[1,0,1] neg_lo:[1,0,0] neg_hi:[1,0,0]
	v_pk_fma_f32 v[2:3], v[8:9], v[72:73], v[2:3] op_sel:[0,1,0] op_sel_hi:[1,1,1] neg_lo:[1,0,0] neg_hi:[1,0,0]
	v_pk_fma_f32 v[4:5], v[8:9], v[74:75], v[4:5] op_sel_hi:[1,0,1] neg_lo:[1,0,0] neg_hi:[1,0,0]
	v_pk_fma_f32 v[6:7], v[8:9], v[74:75], v[6:7] op_sel:[0,1,0] op_sel_hi:[1,1,1] neg_lo:[1,0,0] neg_hi:[1,0,0]
	s_waitcnt lgkmcnt(0)
; #define VPKMUL(d, a, b) asm volatile("v_pk_mul_f32 %0, %1, %2" : "=v"(d) : "v"(a), "v"(b))
; __device__ __forceinline__ void scan_half(const Params& p, LAS unsigned char* lds, int pi, int rh, int pass) {
;     ...
;                 LOADREC(0, 0);
;                 float yp = 0.f, yk0 = 0.f, yk1 = 0.f, yk2 = 0.f, yk3 = 0.f;
;     ...
; #pragma unroll
;                 for (int s = 0; s < 32; ++s) {
;                     const int c = s & 1, pc = c ^ 1;
;                     const float si = __int_as_float(__builtin_amdgcn_readlane(__float_as_int(inv2), s));
;                     f32x2 px, py, t01, t23, t45, t67; float x;
;                     f32x2 vv2; vv2.x = Rv[c]; asm volatile("" : "+v"(vv2));
;                     if (s >= 1) {
;                         VPKMUL(px, P01, Rkk[c][0].xy); VPKMUL(py, P01, Rr[pc][0].xy); VPKFMA(px, P23, Rkk[c][0].zw, px); VPKFMA(py, P23, Rr[pc][0].zw, py);
;                         VPKFMA(px, P45, Rkk[c][1].xy, px); VPKFMA(py, P45, Rr[pc][1].xy, py); VPKFMA(px, P67, Rkk[c][1].zw, px); VPKFMA(py, P67, Rr[pc][1].zw, py);
;                         VADD(x, px.x, px.y); VADD(yp, py.x, py.y);
;                     } else {
;                         VPKMUL(px, P01, Rkk[c][0].xy); VPKFMA(px, P23, Rkk[c][0].zw, px); VPKFMA(px, P45, Rkk[c][1].xy, px); VPKFMA(px, P67, Rkk[c][1].zw, px);
;                         VADD(x, px.x, px.y);
;                     }
;                     asm volatile("" ::: "memory");
;                     if (s + 1 < 32) LOADREC((s + 1) & 1, s + 1);
;                     asm volatile("" ::: "memory");
;                     VPKMULBL(t01, vv2, Rkm[c][0].xy); VPKMULBL(t23, vv2, Rkm[c][0].zw);
;                     VDPP1(x); if (s >= 1) VDPP1(yp);
;                     VPKMULBL(t45, vv2, Rkm[c][1].xy); VPKMULBL(t67, vv2, Rkm[c][1].zw);
;                     VDPP2(x); if (s >= 1) VDPP2(yp);
;                     VPKFMA(P01, P01, Rw[c][0].xy, t01); VPKFMA(P23, P23, Rw[c][0].zw, t23);
;                     VDPP3(x); if (s >= 1) VDPP3(yp);
;                     VPKFMA(P45, P45, Rw[c][1].xy, t45); VPKFMA(P67, P67, Rw[c][1].zw, t67);
;                     if (s >= 1) { if (s - 1 < 8) YSHIFT(yk0); else if (s - 1 < 16) YSHIFT(yk1); else if (s - 1 < 24) YSHIFT(yk2); else YSHIFT(yk3); }
;                     x = x * si;
;                     f32x2 x2; x2.x = x; asm volatile("" : "+v"(x2));
	ds_read_b128 v[64:67], v35 offset:6256
	ds_read_b128 v[76:79], v35 offset:32368
	ds_read_b32 v94, v36 offset:2944
	ds_read_b32 v95, v38 offset:2944
	ds_read_b128 v[68:71], v35 offset:14960
	ds_read_b128 v[72:75], v35 offset:23664
	ds_read_b128 v[88:91], v35 offset:41072
	v_pk_mul_f32 v[8:9], v[0:1], v[48:49] op_sel_hi:[1,0]
	v_pk_mul_f32 v[10:11], v[0:1], v[80:81] op_sel_hi:[1,0]
	v_pk_fma_f32 v[8:9], v[2:3], v[48:49], v[8:9] op_sel:[0,1,0] op_sel_hi:[1,1,1]
	v_pk_fma_f32 v[10:11], v[2:3], v[80:81], v[10:11] op_sel:[0,1,0] op_sel_hi:[1,1,1]
	v_pk_fma_f32 v[8:9], v[4:5], v[50:51], v[8:9] op_sel_hi:[1,0,1]
	v_pk_fma_f32 v[10:11], v[4:5], v[82:83], v[10:11] op_sel_hi:[1,0,1]
	v_pk_fma_f32 v[8:9], v[6:7], v[50:51], v[8:9] op_sel:[0,1,0] op_sel_hi:[1,1,1]
	v_pk_fma_f32 v[10:11], v[6:7], v[82:83], v[10:11] op_sel:[0,1,0] op_sel_hi:[1,1,1]
	v_readlane_b32 s10, v34, 22
	v_pk_mul_f32 v[16:17], v[92:93], v[60:61] op_sel_hi:[1,0]
	v_pk_mul_f32 v[18:19], v[92:93], v[60:61] op_sel:[0,1] op_sel_hi:[1,1]
	v_add_f32_dpp v8, v9, v8 quad_perm:[1,0,3,2] row_mask:0xf bank_mask:0xf bound_ctrl:1
	v_add_f32_dpp v10, v11, v10 quad_perm:[1,0,3,2] row_mask:0xf bank_mask:0xf bound_ctrl:1
	v_pk_mul_f32 v[20:21], v[92:93], v[62:63] op_sel_hi:[1,0]
	v_pk_mul_f32 v[22:23], v[92:93], v[62:63] op_sel:[0,1] op_sel_hi:[1,1]
	v_add_f32_dpp v8, v8, v8 quad_perm:[2,3,0,1] row_mask:0xf bank_mask:0xf bound_ctrl:1
	v_add_f32_dpp v10, v10, v10 quad_perm:[2,3,0,1] row_mask:0xf bank_mask:0xf bound_ctrl:1
	v_pk_fma_f32 v[0:1], v[0:1], v[52:53], v[16:17] op_sel_hi:[1,0,1]
	v_pk_fma_f32 v[2:3], v[2:3], v[52:53], v[18:19] op_sel:[0,1,0] op_sel_hi:[1,1,1]
	v_add_f32_dpp v8, v8, v8 row_ror:4 row_mask:0xf bank_mask:0xf bound_ctrl:1
	v_add_f32_dpp v10, v10, v10 row_ror:4 row_mask:0xf bank_mask:0xf bound_ctrl:1
	v_pk_fma_f32 v[4:5], v[4:5], v[54:55], v[20:21] op_sel_hi:[1,0,1]
	v_add_f32_dpp v8, v8, v8 row_ror:8 row_mask:0xf bank_mask:0xf bound_ctrl:1
	v_mul_f32_e32 v8, s10, v8
	v_add_f32_dpp v101, v10, v10 row_ror:8 row_mask:0xf bank_mask:0x2 bound_ctrl:1
	v_pk_fma_f32 v[6:7], v[6:7], v[54:55], v[22:23] op_sel:[0,1,0] op_sel_hi:[1,1,1]
	v_mov_b32_dpp v9, v8 quad_perm:[1,0,3,2] row_mask:0xf bank_mask:0xf
	v_pk_fma_f32 v[0:1], v[8:9], v[56:57], v[0:1] op_sel_hi:[1,0,1] neg_lo:[1,0,0] neg_hi:[1,0,0]
	v_pk_fma_f32 v[2:3], v[8:9], v[56:57], v[2:3] op_sel:[0,1,0] op_sel_hi:[1,1,1] neg_lo:[1,0,0] neg_hi:[1,0,0]
	v_pk_fma_f32 v[4:5], v[8:9], v[58:59], v[4:5] op_sel_hi:[1,0,1] neg_lo:[1,0,0] neg_hi:[1,0,0]
	v_pk_fma_f32 v[6:7], v[8:9], v[58:59], v[6:7] op_sel:[0,1,0] op_sel_hi:[1,1,1] neg_lo:[1,0,0] neg_hi:[1,0,0]
	s_waitcnt lgkmcnt(0)
	ds_read_b128 v[48:51], v35 offset:6528
	ds_read_b128 v[60:63], v35 offset:32640
	ds_read_b32 v92, v36 offset:3072
	ds_read_b32 v93, v38 offset:3072
	ds_read_b128 v[52:55], v35 offset:15232
	ds_read_b128 v[56:59], v35 offset:23936
	ds_read_b128 v[80:83], v35 offset:41344
	v_pk_mul_f32 v[8:9], v[0:1], v[64:65] op_sel_hi:[1,0]
	v_pk_mul_f32 v[10:11], v[0:1], v[84:85] op_sel_hi:[1,0]
	v_pk_fma_f32 v[8:9], v[2:3], v[64:65], v[8:9] op_sel:[0,1,0] op_sel_hi:[1,1,1]
	v_pk_fma_f32 v[10:11], v[2:3], v[84:85], v[10:11] op_sel:[0,1,0] op_sel_hi:[1,1,1]
	v_pk_fma_f32 v[8:9], v[4:5], v[66:67], v[8:9] op_sel_hi:[1,0,1]
	v_pk_fma_f32 v[10:11], v[4:5], v[86:87], v[10:11] op_sel_hi:[1,0,1]
	v_pk_fma_f32 v[8:9], v[6:7], v[66:67], v[8:9] op_sel:[0,1,0] op_sel_hi:[1,1,1]
	v_pk_fma_f32 v[10:11], v[6:7], v[86:87], v[10:11] op_sel:[0,1,0] op_sel_hi:[1,1,1]
	v_readlane_b32 s10, v34, 23
	v_pk_mul_f32 v[16:17], v[94:95], v[76:77] op_sel_hi:[1,0]
	v_pk_mul_f32 v[18:19], v[94:95], v[76:77] op_sel:[0,1] op_sel_hi:[1,1]
	v_add_f32_dpp v8, v9, v8 quad_perm:[1,0,3,2] row_mask:0xf bank_mask:0xf bound_ctrl:1
	v_add_f32_dpp v10, v11, v10 quad_perm:[1,0,3,2] row_mask:0xf bank_mask:0xf bound_ctrl:1
	v_pk_mul_f32 v[20:21], v[94:95], v[78:79] op_sel_hi:[1,0]
	v_pk_mul_f32 v[22:23], v[94:95], v[78:79] op_sel:[0,1] op_sel_hi:[1,1]
	v_add_f32_dpp v8, v8, v8 quad_perm:[2,3,0,1] row_mask:0xf bank_mask:0xf bound_ctrl:1
	v_add_f32_dpp v10, v10, v10 quad_perm:[2,3,0,1] row_mask:0xf bank_mask:0xf bound_ctrl:1
	v_pk_fma_f32 v[0:1], v[0:1], v[68:69], v[16:17] op_sel_hi:[1,0,1]
	v_pk_fma_f32 v[2:3], v[2:3], v[68:69], v[18:19] op_sel:[0,1,0] op_sel_hi:[1,1,1]
	v_add_f32_dpp v8, v8, v8 row_ror:4 row_mask:0xf bank_mask:0xf bound_ctrl:1
	v_add_f32_dpp v10, v10, v10 row_ror:4 row_mask:0xf bank_mask:0xf bound_ctrl:1
	v_pk_fma_f32 v[4:5], v[4:5], v[70:71], v[20:21] op_sel_hi:[1,0,1]
	v_add_f32_dpp v8, v8, v8 row_ror:8 row_mask:0xf bank_mask:0xf bound_ctrl:1
	v_mul_f32_e32 v8, s10, v8
	v_add_f32_dpp v101, v10, v10 row_ror:8 row_mask:0xf bank_mask:0x4 bound_ctrl:1
	v_pk_fma_f32 v[6:7], v[6:7], v[70:71], v[22:23] op_sel:[0,1,0] op_sel_hi:[1,1,1]
	v_mov_b32_dpp v9, v8 quad_perm:[1,0,3,2] row_mask:0xf bank_mask:0xf
	v_pk_fma_f32 v[0:1], v[8:9], v[72:73], v[0:1] op_sel_hi:[1,0,1] neg_lo:[1,0,0] neg_hi:[1,0,0]
	v_pk_fma_f32 v[2:3], v[8:9], v[72:73], v[2:3] op_sel:[0,1,0] op_sel_hi:[1,1,1] neg_lo:[1,0,0] neg_hi:[1,0,0]
	v_pk_fma_f32 v[4:5], v[8:9], v[74:75], v[4:5] op_sel_hi:[1,0,1] neg_lo:[1,0,0] neg_hi:[1,0,0]
	v_pk_fma_f32 v[6:7], v[8:9], v[74:75], v[6:7] op_sel:[0,1,0] op_sel_hi:[1,1,1] neg_lo:[1,0,0] neg_hi:[1,0,0]
	s_waitcnt lgkmcnt(0)
; #define VPKMUL(d, a, b) asm volatile("v_pk_mul_f32 %0, %1, %2" : "=v"(d) : "v"(a), "v"(b))
; __device__ __forceinline__ void scan_half(const Params& p, LAS unsigned char* lds, int pi, int rh, int pass) {
;     ...
;                 LOADREC(0, 0);
;                 float yp = 0.f, yk0 = 0.f, yk1 = 0.f, yk2 = 0.f, yk3 = 0.f;
;     ...
; #pragma unroll
;                 for (int s = 0; s < 32; ++s) {
;                     const int c = s & 1, pc = c ^ 1;
;                     const float si = __int_as_float(__builtin_amdgcn_readlane(__float_as_int(inv2), s));
;                     f32x2 px, py, t01, t23, t45, t67; float x;
;                     f32x2 vv2; vv2.x = Rv[c]; asm volatile("" : "+v"(vv2));
;                     if (s >= 1) {
;                         VPKMUL(px, P01, Rkk[c][0].xy); VPKMUL(py, P01, Rr[pc][0].xy); VPKFMA(px, P23, Rkk[c][0].zw, px); VPKFMA(py, P23, Rr[pc][0].zw, py);
;                         VPKFMA(px, P45, Rkk[c][1].xy, px); VPKFMA(py, P45, Rr[pc][1].xy, py); VPKFMA(px, P67, Rkk[c][1].zw, px); VPKFMA(py, P67, Rr[pc][1].zw, py);
;                         VADD(x, px.x, px.y); VADD(yp, py.x, py.y);
;                     } else {
;                         VPKMUL(px, P01, Rkk[c][0].xy); VPKFMA(px, P23, Rkk[c][0].zw, px); VPKFMA(px, P45, Rkk[c][1].xy, px); VPKFMA(px, P67, Rkk[c][1].zw, px);
;                         VADD(x, px.x, px.y);
;                     }
;                     asm volatile("" ::: "memory");
;                     if (s + 1 < 32) LOADREC((s + 1) & 1, s + 1);
;                     asm volatile("" ::: "memory");
;                     VPKMULBL(t01, vv2, Rkm[c][0].xy); VPKMULBL(t23, vv2, Rkm[c][0].zw);
;                     VDPP1(x); if (s >= 1) VDPP1(yp);
;                     VPKMULBL(t45, vv2, Rkm[c][1].xy); VPKMULBL(t67, vv2, Rkm[c][1].zw);
;                     VDPP2(x); if (s >= 1) VDPP2(yp);
;                     VPKFMA(P01, P01, Rw[c][0].xy, t01); VPKFMA(P23, P23, Rw[c][0].zw, t23);
;                     VDPP3(x); if (s >= 1) VDPP3(yp);
;                     VPKFMA(P45, P45, Rw[c][1].xy, t45); VPKFMA(P67, P67, Rw[c][1].zw, t67);
;                     if (s >= 1) { if (s - 1 < 8) YSHIFT(yk0); else if (s - 1 < 16) YSHIFT(yk1); else if (s - 1 < 24) YSHIFT(yk2); else YSHIFT(yk3); }
;                     x = x * si;
;                     f32x2 x2; x2.x = x; asm volatile("" : "+v"(x2));
	ds_read_b128 v[64:67], v35 offset:6800
	ds_read_b128 v[76:79], v35 offset:32912
	ds_read_b32 v94, v36 offset:3200
	ds_read_b32 v95, v38 offset:3200
	ds_read_b128 v[68:71], v35 offset:15504
	ds_read_b128 v[72:75], v35 offset:24208
	ds_read_b128 v[84:87], v35 offset:41616
	v_pk_mul_f32 v[8:9], v[0:1], v[48:49] op_sel_hi:[1,0]
	v_pk_mul_f32 v[10:11], v[0:1], v[88:89] op_sel_hi:[1,0]
	v_pk_fma_f32 v[8:9], v[2:3], v[48:49], v[8:9] op_sel:[0,1,0] op_sel_hi:[1,1,1]
	v_pk_fma_f32 v[10:11], v[2:3], v[88:89], v[10:11] op_sel:[0,1,0] op_sel_hi:[1,1,1]
	v_pk_fma_f32 v[8:9], v[4:5], v[50:51], v[8:9] op_sel_hi:[1,0,1]
	v_pk_fma_f32 v[10:11], v[4:5], v[90:91], v[10:11] op_sel_hi:[1,0,1]
	v_pk_fma_f32 v[8:9], v[6:7], v[50:51], v[8:9] op_sel:[0,1,0] op_sel_hi:[1,1,1]
	v_pk_fma_f32 v[10:11], v[6:7], v[90:91], v[10:11] op_sel:[0,1,0] op_sel_hi:[1,1,1]
	v_readlane_b32 s10, v34, 24
	v_pk_mul_f32 v[16:17], v[92:93], v[60:61] op_sel_hi:[1,0]
	v_pk_mul_f32 v[18:19], v[92:93], v[60:61] op_sel:[0,1] op_sel_hi:[1,1]
	v_add_f32_dpp v8, v9, v8 quad_perm:[1,0,3,2] row_mask:0xf bank_mask:0xf bound_ctrl:1
	v_add_f32_dpp v10, v11, v10 quad_perm:[1,0,3,2] row_mask:0xf bank_mask:0xf bound_ctrl:1
	v_pk_mul_f32 v[20:21], v[92:93], v[62:63] op_sel_hi:[1,0]
	v_pk_mul_f32 v[22:23], v[92:93], v[62:63] op_sel:[0,1] op_sel_hi:[1,1]
	v_add_f32_dpp v8, v8, v8 quad_perm:[2,3,0,1] row_mask:0xf bank_mask:0xf bound_ctrl:1
	v_add_f32_dpp v10, v10, v10 quad_perm:[2,3,0,1] row_mask:0xf bank_mask:0xf bound_ctrl:1
	v_pk_fma_f32 v[0:1], v[0:1], v[52:53], v[16:17] op_sel_hi:[1,0,1]
	v_pk_fma_f32 v[2:3], v[2:3], v[52:53], v[18:19] op_sel:[0,1,0] op_sel_hi:[1,1,1]
	v_add_f32_dpp v8, v8, v8 row_ror:4 row_mask:0xf bank_mask:0xf bound_ctrl:1
	v_add_f32_dpp v10, v10, v10 row_ror:4 row_mask:0xf bank_mask:0xf bound_ctrl:1
	v_pk_fma_f32 v[4:5], v[4:5], v[54:55], v[20:21] op_sel_hi:[1,0,1]
	v_add_f32_dpp v8, v8, v8 row_ror:8 row_mask:0xf bank_mask:0xf bound_ctrl:1
	v_mul_f32_e32 v8, s10, v8
	v_add_f32_dpp v101, v10, v10 row_ror:8 row_mask:0xf bank_mask:0x8 bound_ctrl:1
	v_pk_fma_f32 v[6:7], v[6:7], v[54:55], v[22:23] op_sel:[0,1,0] op_sel_hi:[1,1,1]
	v_mov_b32_dpp v9, v8 quad_perm:[1,0,3,2] row_mask:0xf bank_mask:0xf
	v_pk_fma_f32 v[0:1], v[8:9], v[56:57], v[0:1] op_sel_hi:[1,0,1] neg_lo:[1,0,0] neg_hi:[1,0,0]
	v_pk_fma_f32 v[2:3], v[8:9], v[56:57], v[2:3] op_sel:[0,1,0] op_sel_hi:[1,1,1] neg_lo:[1,0,0] neg_hi:[1,0,0]
	v_pk_fma_f32 v[4:5], v[8:9], v[58:59], v[4:5] op_sel_hi:[1,0,1] neg_lo:[1,0,0] neg_hi:[1,0,0]
	v_pk_fma_f32 v[6:7], v[8:9], v[58:59], v[6:7] op_sel:[0,1,0] op_sel_hi:[1,1,1] neg_lo:[1,0,0] neg_hi:[1,0,0]
	s_waitcnt lgkmcnt(0)
	ds_read_b128 v[48:51], v35 offset:7072
	ds_read_b128 v[60:63], v35 offset:33184
	ds_read_b32 v92, v36 offset:3328
	ds_read_b32 v93, v38 offset:3328
	ds_read_b128 v[52:55], v35 offset:15776
	ds_read_b128 v[56:59], v35 offset:24480
	ds_read_b128 v[88:91], v35 offset:41888
	v_pk_mul_f32 v[8:9], v[0:1], v[64:65] op_sel_hi:[1,0]
	v_pk_mul_f32 v[10:11], v[0:1], v[80:81] op_sel_hi:[1,0]
	v_pk_fma_f32 v[8:9], v[2:3], v[64:65], v[8:9] op_sel:[0,1,0] op_sel_hi:[1,1,1]
	v_pk_fma_f32 v[10:11], v[2:3], v[80:81], v[10:11] op_sel:[0,1,0] op_sel_hi:[1,1,1]
	v_pk_fma_f32 v[8:9], v[4:5], v[66:67], v[8:9] op_sel_hi:[1,0,1]
	v_pk_fma_f32 v[10:11], v[4:5], v[82:83], v[10:11] op_sel_hi:[1,0,1]
	v_pk_fma_f32 v[8:9], v[6:7], v[66:67], v[8:9] op_sel:[0,1,0] op_sel_hi:[1,1,1]
	v_pk_fma_f32 v[10:11], v[6:7], v[82:83], v[10:11] op_sel:[0,1,0] op_sel_hi:[1,1,1]
	v_readlane_b32 s10, v34, 25
	v_pk_mul_f32 v[16:17], v[94:95], v[76:77] op_sel_hi:[1,0]
	v_pk_mul_f32 v[18:19], v[94:95], v[76:77] op_sel:[0,1] op_sel_hi:[1,1]
	v_add_f32_dpp v8, v9, v8 quad_perm:[1,0,3,2] row_mask:0xf bank_mask:0xf bound_ctrl:1
	v_add_f32_dpp v10, v11, v10 quad_perm:[1,0,3,2] row_mask:0xf bank_mask:0xf bound_ctrl:1
	v_pk_mul_f32 v[20:21], v[94:95], v[78:79] op_sel_hi:[1,0]
	v_pk_mul_f32 v[22:23], v[94:95], v[78:79] op_sel:[0,1] op_sel_hi:[1,1]
	v_add_f32_dpp v8, v8, v8 quad_perm:[2,3,0,1] row_mask:0xf bank_mask:0xf bound_ctrl:1
	v_add_f32_dpp v10, v10, v10 quad_perm:[2,3,0,1] row_mask:0xf bank_mask:0xf bound_ctrl:1
	v_pk_fma_f32 v[0:1], v[0:1], v[68:69], v[16:17] op_sel_hi:[1,0,1]
	v_pk_fma_f32 v[2:3], v[2:3], v[68:69], v[18:19] op_sel:[0,1,0] op_sel_hi:[1,1,1]
	v_add_f32_dpp v8, v8, v8 row_ror:4 row_mask:0xf bank_mask:0xf bound_ctrl:1
	v_add_f32_dpp v10, v10, v10 row_ror:4 row_mask:0xf bank_mask:0xf bound_ctrl:1
	v_pk_fma_f32 v[4:5], v[4:5], v[70:71], v[20:21] op_sel_hi:[1,0,1]
	v_add_f32_dpp v8, v8, v8 row_ror:8 row_mask:0xf bank_mask:0xf bound_ctrl:1
	v_mul_f32_e32 v8, s10, v8
	v_add_f32_dpp v102, v10, v10 row_ror:8 row_mask:0xf bank_mask:0x1 bound_ctrl:1
	v_pk_fma_f32 v[6:7], v[6:7], v[70:71], v[22:23] op_sel:[0,1,0] op_sel_hi:[1,1,1]
	v_mov_b32_dpp v9, v8 quad_perm:[1,0,3,2] row_mask:0xf bank_mask:0xf
	v_pk_fma_f32 v[0:1], v[8:9], v[72:73], v[0:1] op_sel_hi:[1,0,1] neg_lo:[1,0,0] neg_hi:[1,0,0]
	v_pk_fma_f32 v[2:3], v[8:9], v[72:73], v[2:3] op_sel:[0,1,0] op_sel_hi:[1,1,1] neg_lo:[1,0,0] neg_hi:[1,0,0]
	v_pk_fma_f32 v[4:5], v[8:9], v[74:75], v[4:5] op_sel_hi:[1,0,1] neg_lo:[1,0,0] neg_hi:[1,0,0]
	v_pk_fma_f32 v[6:7], v[8:9], v[74:75], v[6:7] op_sel:[0,1,0] op_sel_hi:[1,1,1] neg_lo:[1,0,0] neg_hi:[1,0,0]
	s_waitcnt lgkmcnt(0)
; #define VPKMUL(d, a, b) asm volatile("v_pk_mul_f32 %0, %1, %2" : "=v"(d) : "v"(a), "v"(b))
; __device__ __forceinline__ void scan_half(const Params& p, LAS unsigned char* lds, int pi, int rh, int pass) {
;     ...
;                 LOADREC(0, 0);
;                 float yp = 0.f, yk0 = 0.f, yk1 = 0.f, yk2 = 0.f, yk3 = 0.f;
;     ...
; #pragma unroll
;                 for (int s = 0; s < 32; ++s) {
;                     const int c = s & 1, pc = c ^ 1;
;                     const float si = __int_as_float(__builtin_amdgcn_readlane(__float_as_int(inv2), s));
;                     f32x2 px, py, t01, t23, t45, t67; float x;
;                     f32x2 vv2; vv2.x = Rv[c]; asm volatile("" : "+v"(vv2));
;                     if (s >= 1) {
;                         VPKMUL(px, P01, Rkk[c][0].xy); VPKMUL(py, P01, Rr[pc][0].xy); VPKFMA(px, P23, Rkk[c][0].zw, px); VPKFMA(py, P23, Rr[pc][0].zw, py);
;                         VPKFMA(px, P45, Rkk[c][1].xy, px); VPKFMA(py, P45, Rr[pc][1].xy, py); VPKFMA(px, P67, Rkk[c][1].zw, px); VPKFMA(py, P67, Rr[pc][1].zw, py);
;                         VADD(x, px.x, px.y); VADD(yp, py.x, py.y);
;                     } else {
;                         VPKMUL(px, P01, Rkk[c][0].xy); VPKFMA(px, P23, Rkk[c][0].zw, px); VPKFMA(px, P45, Rkk[c][1].xy, px); VPKFMA(px, P67, Rkk[c][1].zw, px);
;                         VADD(x, px.x, px.y);
;                     }
;                     asm volatile("" ::: "memory");
;                     if (s + 1 < 32) LOADREC((s + 1) & 1, s + 1);
;                     asm volatile("" ::: "memory");
;                     VPKMULBL(t01, vv2, Rkm[c][0].xy); VPKMULBL(t23, vv2, Rkm[c][0].zw);
;                     VDPP1(x); if (s >= 1) VDPP1(yp);
;                     VPKMULBL(t45, vv2, Rkm[c][1].xy); VPKMULBL(t67, vv2, Rkm[c][1].zw);
;                     VDPP2(x); if (s >= 1) VDPP2(yp);
;                     VPKFMA(P01, P01, Rw[c][0].xy, t01); VPKFMA(P23, P23, Rw[c][0].zw, t23);
;                     VDPP3(x); if (s >= 1) VDPP3(yp);
;                     VPKFMA(P45, P45, Rw[c][1].xy, t45); VPKFMA(P67, P67, Rw[c][1].zw, t67);
;                     if (s >= 1) { if (s - 1 < 8) YSHIFT(yk0); else if (s - 1 < 16) YSHIFT(yk1); else if (s - 1 < 24) YSHIFT(yk2); else YSHIFT(yk3); }
;                     x = x * si;
;                     f32x2 x2; x2.x = x; asm volatile("" : "+v"(x2));
	ds_read_b128 v[64:67], v35 offset:7344
	ds_read_b128 v[76:79], v35 offset:33456
	ds_read_b32 v94, v36 offset:3456
	ds_read_b32 v95, v38 offset:3456
	ds_read_b128 v[68:71], v35 offset:16048
	ds_read_b128 v[72:75], v35 offset:24752
	ds_read_b128 v[80:83], v35 offset:42160
	v_pk_mul_f32 v[8:9], v[0:1], v[48:49] op_sel_hi:[1,0]
	v_pk_mul_f32 v[10:11], v[0:1], v[84:85] op_sel_hi:[1,0]
	v_pk_fma_f32 v[8:9], v[2:3], v[48:49], v[8:9] op_sel:[0,1,0] op_sel_hi:[1,1,1]
	v_pk_fma_f32 v[10:11], v[2:3], v[84:85], v[10:11] op_sel:[0,1,0] op_sel_hi:[1,1,1]
	v_pk_fma_f32 v[8:9], v[4:5], v[50:51], v[8:9] op_sel_hi:[1,0,1]
	v_pk_fma_f32 v[10:11], v[4:5], v[86:87], v[10:11] op_sel_hi:[1,0,1]
	v_pk_fma_f32 v[8:9], v[6:7], v[50:51], v[8:9] op_sel:[0,1,0] op_sel_hi:[1,1,1]
	v_pk_fma_f32 v[10:11], v[6:7], v[86:87], v[10:11] op_sel:[0,1,0] op_sel_hi:[1,1,1]
	v_readlane_b32 s10, v34, 26
	v_pk_mul_f32 v[16:17], v[92:93], v[60:61] op_sel_hi:[1,0]
	v_pk_mul_f32 v[18:19], v[92:93], v[60:61] op_sel:[0,1] op_sel_hi:[1,1]
	v_add_f32_dpp v8, v9, v8 quad_perm:[1,0,3,2] row_mask:0xf bank_mask:0xf bound_ctrl:1
	v_add_f32_dpp v10, v11, v10 quad_perm:[1,0,3,2] row_mask:0xf bank_mask:0xf bound_ctrl:1
	v_pk_mul_f32 v[20:21], v[92:93], v[62:63] op_sel_hi:[1,0]
	v_pk_mul_f32 v[22:23], v[92:93], v[62:63] op_sel:[0,1] op_sel_hi:[1,1]
	v_add_f32_dpp v8, v8, v8 quad_perm:[2,3,0,1] row_mask:0xf bank_mask:0xf bound_ctrl:1
	v_add_f32_dpp v10, v10, v10 quad_perm:[2,3,0,1] row_mask:0xf bank_mask:0xf bound_ctrl:1
	v_pk_fma_f32 v[0:1], v[0:1], v[52:53], v[16:17] op_sel_hi:[1,0,1]
	v_pk_fma_f32 v[2:3], v[2:3], v[52:53], v[18:19] op_sel:[0,1,0] op_sel_hi:[1,1,1]
	v_add_f32_dpp v8, v8, v8 row_ror:4 row_mask:0xf bank_mask:0xf bound_ctrl:1
	v_add_f32_dpp v10, v10, v10 row_ror:4 row_mask:0xf bank_mask:0xf bound_ctrl:1
	v_pk_fma_f32 v[4:5], v[4:5], v[54:55], v[20:21] op_sel_hi:[1,0,1]
	v_add_f32_dpp v8, v8, v8 row_ror:8 row_mask:0xf bank_mask:0xf bound_ctrl:1
	v_mul_f32_e32 v8, s10, v8
	v_add_f32_dpp v102, v10, v10 row_ror:8 row_mask:0xf bank_mask:0x2 bound_ctrl:1
	v_pk_fma_f32 v[6:7], v[6:7], v[54:55], v[22:23] op_sel:[0,1,0] op_sel_hi:[1,1,1]
	v_mov_b32_dpp v9, v8 quad_perm:[1,0,3,2] row_mask:0xf bank_mask:0xf
	v_pk_fma_f32 v[0:1], v[8:9], v[56:57], v[0:1] op_sel_hi:[1,0,1] neg_lo:[1,0,0] neg_hi:[1,0,0]
	v_pk_fma_f32 v[2:3], v[8:9], v[56:57], v[2:3] op_sel:[0,1,0] op_sel_hi:[1,1,1] neg_lo:[1,0,0] neg_hi:[1,0,0]
	v_pk_fma_f32 v[4:5], v[8:9], v[58:59], v[4:5] op_sel_hi:[1,0,1] neg_lo:[1,0,0] neg_hi:[1,0,0]
	v_pk_fma_f32 v[6:7], v[8:9], v[58:59], v[6:7] op_sel:[0,1,0] op_sel_hi:[1,1,1] neg_lo:[1,0,0] neg_hi:[1,0,0]
	s_waitcnt lgkmcnt(0)
	ds_read_b128 v[48:51], v35 offset:7616
	ds_read_b128 v[60:63], v35 offset:33728
	ds_read_b32 v92, v36 offset:3584
	ds_read_b32 v93, v38 offset:3584
	ds_read_b128 v[52:55], v35 offset:16320
	ds_read_b128 v[56:59], v35 offset:25024
	ds_read_b128 v[84:87], v35 offset:42432
	v_pk_mul_f32 v[8:9], v[0:1], v[64:65] op_sel_hi:[1,0]
	v_pk_mul_f32 v[10:11], v[0:1], v[88:89] op_sel_hi:[1,0]
	v_pk_fma_f32 v[8:9], v[2:3], v[64:65], v[8:9] op_sel:[0,1,0] op_sel_hi:[1,1,1]
	v_pk_fma_f32 v[10:11], v[2:3], v[88:89], v[10:11] op_sel:[0,1,0] op_sel_hi:[1,1,1]
	v_pk_fma_f32 v[8:9], v[4:5], v[66:67], v[8:9] op_sel_hi:[1,0,1]
	v_pk_fma_f32 v[10:11], v[4:5], v[90:91], v[10:11] op_sel_hi:[1,0,1]
	v_pk_fma_f32 v[8:9], v[6:7], v[66:67], v[8:9] op_sel:[0,1,0] op_sel_hi:[1,1,1]
	v_pk_fma_f32 v[10:11], v[6:7], v[90:91], v[10:11] op_sel:[0,1,0] op_sel_hi:[1,1,1]
	v_readlane_b32 s10, v34, 27
	v_pk_mul_f32 v[16:17], v[94:95], v[76:77] op_sel_hi:[1,0]
	v_pk_mul_f32 v[18:19], v[94:95], v[76:77] op_sel:[0,1] op_sel_hi:[1,1]
	v_add_f32_dpp v8, v9, v8 quad_perm:[1,0,3,2] row_mask:0xf bank_mask:0xf bound_ctrl:1
	v_add_f32_dpp v10, v11, v10 quad_perm:[1,0,3,2] row_mask:0xf bank_mask:0xf bound_ctrl:1
	v_pk_mul_f32 v[20:21], v[94:95], v[78:79] op_sel_hi:[1,0]
	v_pk_mul_f32 v[22:23], v[94:95], v[78:79] op_sel:[0,1] op_sel_hi:[1,1]
	v_add_f32_dpp v8, v8, v8 quad_perm:[2,3,0,1] row_mask:0xf bank_mask:0xf bound_ctrl:1
	v_add_f32_dpp v10, v10, v10 quad_perm:[2,3,0,1] row_mask:0xf bank_mask:0xf bound_ctrl:1
	v_pk_fma_f32 v[0:1], v[0:1], v[68:69], v[16:17] op_sel_hi:[1,0,1]
	v_pk_fma_f32 v[2:3], v[2:3], v[68:69], v[18:19] op_sel:[0,1,0] op_sel_hi:[1,1,1]
	v_add_f32_dpp v8, v8, v8 row_ror:4 row_mask:0xf bank_mask:0xf bound_ctrl:1
	v_add_f32_dpp v10, v10, v10 row_ror:4 row_mask:0xf bank_mask:0xf bound_ctrl:1
	v_pk_fma_f32 v[4:5], v[4:5], v[70:71], v[20:21] op_sel_hi:[1,0,1]
	v_add_f32_dpp v8, v8, v8 row_ror:8 row_mask:0xf bank_mask:0xf bound_ctrl:1
	v_mul_f32_e32 v8, s10, v8
	v_add_f32_dpp v102, v10, v10 row_ror:8 row_mask:0xf bank_mask:0x4 bound_ctrl:1
	v_pk_fma_f32 v[6:7], v[6:7], v[70:71], v[22:23] op_sel:[0,1,0] op_sel_hi:[1,1,1]
	v_mov_b32_dpp v9, v8 quad_perm:[1,0,3,2] row_mask:0xf bank_mask:0xf
	v_pk_fma_f32 v[0:1], v[8:9], v[72:73], v[0:1] op_sel_hi:[1,0,1] neg_lo:[1,0,0] neg_hi:[1,0,0]
	v_pk_fma_f32 v[2:3], v[8:9], v[72:73], v[2:3] op_sel:[0,1,0] op_sel_hi:[1,1,1] neg_lo:[1,0,0] neg_hi:[1,0,0]
	v_pk_fma_f32 v[4:5], v[8:9], v[74:75], v[4:5] op_sel_hi:[1,0,1] neg_lo:[1,0,0] neg_hi:[1,0,0]
	v_pk_fma_f32 v[6:7], v[8:9], v[74:75], v[6:7] op_sel:[0,1,0] op_sel_hi:[1,1,1] neg_lo:[1,0,0] neg_hi:[1,0,0]
	s_waitcnt lgkmcnt(0)
; __device__ __forceinline__ void scan_half(const Params& p, LAS unsigned char* lds, int pi, int rh, int pass) {
;     ...
;                 for (int s = 0; s < 32; ++s) {
;                     const int c = s & 1, pc = c ^ 1;
;                     const float si = __int_as_float(__builtin_amdgcn_readlane(__float_as_int(inv2), s));
;                     f32x2 px, py, t01, t23, t45, t67; float x;
;                     f32x2 vv2; vv2.x = Rv[c]; asm volatile("" : "+v"(vv2));
;                     if (s >= 1) {
;                         VPKMUL(px, P01, Rkk[c][0].xy); VPKMUL(py, P01, Rr[pc][0].xy); VPKFMA(px, P23, Rkk[c][0].zw, px); VPKFMA(py, P23, Rr[pc][0].zw, py);
;                         VPKFMA(px, P45, Rkk[c][1].xy, px); VPKFMA(py, P45, Rr[pc][1].xy, py); VPKFMA(px, P67, Rkk[c][1].zw, px); VPKFMA(py, P67, Rr[pc][1].zw, py);
;                         VADD(x, px.x, px.y); VADD(yp, py.x, py.y);
;                     } else {
;                         VPKMUL(px, P01, Rkk[c][0].xy); VPKFMA(px, P23, Rkk[c][0].zw, px); VPKFMA(px, P45, Rkk[c][1].xy, px); VPKFMA(px, P67, Rkk[c][1].zw, px);
;                         VADD(x, px.x, px.y);
;                     }
;                     asm volatile("" ::: "memory");
;                     if (s + 1 < 32) LOADREC((s + 1) & 1, s + 1);
;                     asm volatile("" ::: "memory");
;                     VPKMULBL(t01, vv2, Rkm[c][0].xy); VPKMULBL(t23, vv2, Rkm[c][0].zw);
;                     VDPP1(x); if (s >= 1) VDPP1(yp);
;                     VPKMULBL(t45, vv2, Rkm[c][1].xy); VPKMULBL(t67, vv2, Rkm[c][1].zw);
;                     VDPP2(x); if (s >= 1) VDPP2(yp);
;                     VPKFMA(P01, P01, Rw[c][0].xy, t01); VPKFMA(P23, P23, Rw[c][0].zw, t23);
;                     VDPP3(x); if (s >= 1) VDPP3(yp);
;                     VPKFMA(P45, P45, Rw[c][1].xy, t45); VPKFMA(P67, P67, Rw[c][1].zw, t67);
;                     if (s >= 1) { if (s - 1 < 8) YSHIFT(yk0); else if (s - 1 < 16) YSHIFT(yk1); else if (s - 1 < 24) YSHIFT(yk2); else YSHIFT(yk3); }
;                     x = x * si;
;                     f32x2 x2; x2.x = x; asm volatile("" : "+v"(x2));
;                     VPKNFMABL(P01, x2, Rka[c][0].xy, P01); VPKNFMABL(P23, x2, Rka[c][0].zw, P23); VPKNFMABL(P45, x2, Rka[c][1].xy, P45); VPKNFMABL(P67, x2, Rka[c][1].zw, P67);
;                 }
	ds_read_b128 v[64:67], v35 offset:7888
	ds_read_b128 v[76:79], v35 offset:34000
	ds_read_b32 v94, v36 offset:3712
	ds_read_b32 v95, v38 offset:3712
	ds_read_b128 v[68:71], v35 offset:16592
	ds_read_b128 v[72:75], v35 offset:25296
	ds_read_b128 v[88:91], v35 offset:42704
	v_pk_mul_f32 v[8:9], v[0:1], v[48:49] op_sel_hi:[1,0]
	v_pk_mul_f32 v[10:11], v[0:1], v[80:81] op_sel_hi:[1,0]
	v_pk_fma_f32 v[8:9], v[2:3], v[48:49], v[8:9] op_sel:[0,1,0] op_sel_hi:[1,1,1]
	v_pk_fma_f32 v[10:11], v[2:3], v[80:81], v[10:11] op_sel:[0,1,0] op_sel_hi:[1,1,1]
	v_pk_fma_f32 v[8:9], v[4:5], v[50:51], v[8:9] op_sel_hi:[1,0,1]
	v_pk_fma_f32 v[10:11], v[4:5], v[82:83], v[10:11] op_sel_hi:[1,0,1]
	v_pk_fma_f32 v[8:9], v[6:7], v[50:51], v[8:9] op_sel:[0,1,0] op_sel_hi:[1,1,1]
	v_pk_fma_f32 v[10:11], v[6:7], v[82:83], v[10:11] op_sel:[0,1,0] op_sel_hi:[1,1,1]
	v_readlane_b32 s10, v34, 28
	v_pk_mul_f32 v[16:17], v[92:93], v[60:61] op_sel_hi:[1,0]
	v_pk_mul_f32 v[18:19], v[92:93], v[60:61] op_sel:[0,1] op_sel_hi:[1,1]
	v_add_f32_dpp v8, v9, v8 quad_perm:[1,0,3,2] row_mask:0xf bank_mask:0xf bound_ctrl:1
	v_add_f32_dpp v10, v11, v10 quad_perm:[1,0,3,2] row_mask:0xf bank_mask:0xf bound_ctrl:1
	v_pk_mul_f32 v[20:21], v[92:93], v[62:63] op_sel_hi:[1,0]
	v_pk_mul_f32 v[22:23], v[92:93], v[62:63] op_sel:[0,1] op_sel_hi:[1,1]
	v_add_f32_dpp v8, v8, v8 quad_perm:[2,3,0,1] row_mask:0xf bank_mask:0xf bound_ctrl:1
	v_add_f32_dpp v10, v10, v10 quad_perm:[2,3,0,1] row_mask:0xf bank_mask:0xf bound_ctrl:1
	v_pk_fma_f32 v[0:1], v[0:1], v[52:53], v[16:17] op_sel_hi:[1,0,1]
	v_pk_fma_f32 v[2:3], v[2:3], v[52:53], v[18:19] op_sel:[0,1,0] op_sel_hi:[1,1,1]
	v_add_f32_dpp v8, v8, v8 row_ror:4 row_mask:0xf bank_mask:0xf bound_ctrl:1
	v_add_f32_dpp v10, v10, v10 row_ror:4 row_mask:0xf bank_mask:0xf bound_ctrl:1
	v_pk_fma_f32 v[4:5], v[4:5], v[54:55], v[20:21] op_sel_hi:[1,0,1]
	v_add_f32_dpp v8, v8, v8 row_ror:8 row_mask:0xf bank_mask:0xf bound_ctrl:1
	v_mul_f32_e32 v8, s10, v8
	v_add_f32_dpp v102, v10, v10 row_ror:8 row_mask:0xf bank_mask:0x8 bound_ctrl:1
	v_pk_fma_f32 v[6:7], v[6:7], v[54:55], v[22:23] op_sel:[0,1,0] op_sel_hi:[1,1,1]
	v_mov_b32_dpp v9, v8 quad_perm:[1,0,3,2] row_mask:0xf bank_mask:0xf
	v_pk_fma_f32 v[0:1], v[8:9], v[56:57], v[0:1] op_sel_hi:[1,0,1] neg_lo:[1,0,0] neg_hi:[1,0,0]
	v_pk_fma_f32 v[2:3], v[8:9], v[56:57], v[2:3] op_sel:[0,1,0] op_sel_hi:[1,1,1] neg_lo:[1,0,0] neg_hi:[1,0,0]
	v_pk_fma_f32 v[4:5], v[8:9], v[58:59], v[4:5] op_sel_hi:[1,0,1] neg_lo:[1,0,0] neg_hi:[1,0,0]
	v_pk_fma_f32 v[6:7], v[8:9], v[58:59], v[6:7] op_sel:[0,1,0] op_sel_hi:[1,1,1] neg_lo:[1,0,0] neg_hi:[1,0,0]
	s_waitcnt lgkmcnt(0)
	ds_read_b128 v[48:51], v35 offset:8160
	ds_read_b128 v[60:63], v35 offset:34272
	ds_read_b32 v92, v36 offset:3840
	ds_read_b32 v93, v38 offset:3840
	ds_read_b128 v[52:55], v35 offset:16864
	ds_read_b128 v[56:59], v35 offset:25568
	ds_read_b128 v[80:83], v35 offset:42976
	v_pk_mul_f32 v[8:9], v[0:1], v[64:65] op_sel_hi:[1,0]
	v_pk_mul_f32 v[10:11], v[0:1], v[84:85] op_sel_hi:[1,0]
	v_pk_fma_f32 v[8:9], v[2:3], v[64:65], v[8:9] op_sel:[0,1,0] op_sel_hi:[1,1,1]
	v_pk_fma_f32 v[10:11], v[2:3], v[84:85], v[10:11] op_sel:[0,1,0] op_sel_hi:[1,1,1]
	v_pk_fma_f32 v[8:9], v[4:5], v[66:67], v[8:9] op_sel_hi:[1,0,1]
	v_pk_fma_f32 v[10:11], v[4:5], v[86:87], v[10:11] op_sel_hi:[1,0,1]
	v_pk_fma_f32 v[8:9], v[6:7], v[66:67], v[8:9] op_sel:[0,1,0] op_sel_hi:[1,1,1]
	v_pk_fma_f32 v[10:11], v[6:7], v[86:87], v[10:11] op_sel:[0,1,0] op_sel_hi:[1,1,1]
	v_readlane_b32 s10, v34, 29
	v_pk_mul_f32 v[16:17], v[94:95], v[76:77] op_sel_hi:[1,0]
	v_pk_mul_f32 v[18:19], v[94:95], v[76:77] op_sel:[0,1] op_sel_hi:[1,1]
	v_add_f32_dpp v8, v9, v8 quad_perm:[1,0,3,2] row_mask:0xf bank_mask:0xf bound_ctrl:1
	v_add_f32_dpp v10, v11, v10 quad_perm:[1,0,3,2] row_mask:0xf bank_mask:0xf bound_ctrl:1
	v_pk_mul_f32 v[20:21], v[94:95], v[78:79] op_sel_hi:[1,0]
	v_pk_mul_f32 v[22:23], v[94:95], v[78:79] op_sel:[0,1] op_sel_hi:[1,1]
	v_add_f32_dpp v8, v8, v8 quad_perm:[2,3,0,1] row_mask:0xf bank_mask:0xf bound_ctrl:1
	v_add_f32_dpp v10, v10, v10 quad_perm:[2,3,0,1] row_mask:0xf bank_mask:0xf bound_ctrl:1
	v_pk_fma_f32 v[0:1], v[0:1], v[68:69], v[16:17] op_sel_hi:[1,0,1]
	v_pk_fma_f32 v[2:3], v[2:3], v[68:69], v[18:19] op_sel:[0,1,0] op_sel_hi:[1,1,1]
	v_add_f32_dpp v8, v8, v8 row_ror:4 row_mask:0xf bank_mask:0xf bound_ctrl:1
	v_add_f32_dpp v10, v10, v10 row_ror:4 row_mask:0xf bank_mask:0xf bound_ctrl:1
	v_pk_fma_f32 v[4:5], v[4:5], v[70:71], v[20:21] op_sel_hi:[1,0,1]
	v_add_f32_dpp v8, v8, v8 row_ror:8 row_mask:0xf bank_mask:0xf bound_ctrl:1
	v_mul_f32_e32 v8, s10, v8
	v_add_f32_dpp v103, v10, v10 row_ror:8 row_mask:0xf bank_mask:0x1 bound_ctrl:1
	v_pk_fma_f32 v[6:7], v[6:7], v[70:71], v[22:23] op_sel:[0,1,0] op_sel_hi:[1,1,1]
	v_mov_b32_dpp v9, v8 quad_perm:[1,0,3,2] row_mask:0xf bank_mask:0xf
	v_pk_fma_f32 v[0:1], v[8:9], v[72:73], v[0:1] op_sel_hi:[1,0,1] neg_lo:[1,0,0] neg_hi:[1,0,0]
	v_pk_fma_f32 v[2:3], v[8:9], v[72:73], v[2:3] op_sel:[0,1,0] op_sel_hi:[1,1,1] neg_lo:[1,0,0] neg_hi:[1,0,0]
	v_pk_fma_f32 v[4:5], v[8:9], v[74:75], v[4:5] op_sel_hi:[1,0,1] neg_lo:[1,0,0] neg_hi:[1,0,0]
	v_pk_fma_f32 v[6:7], v[8:9], v[74:75], v[6:7] op_sel:[0,1,0] op_sel_hi:[1,1,1] neg_lo:[1,0,0] neg_hi:[1,0,0]
	s_waitcnt lgkmcnt(0)
; __device__ __forceinline__ void scan_half(const Params& p, LAS unsigned char* lds, int pi, int rh, int pass) {
;     ...
;                 for (int s = 0; s < 32; ++s) {
;                     const int c = s & 1, pc = c ^ 1;
;                     const float si = __int_as_float(__builtin_amdgcn_readlane(__float_as_int(inv2), s));
;                     f32x2 px, py, t01, t23, t45, t67; float x;
;                     f32x2 vv2; vv2.x = Rv[c]; asm volatile("" : "+v"(vv2));
;                     if (s >= 1) {
;                         VPKMUL(px, P01, Rkk[c][0].xy); VPKMUL(py, P01, Rr[pc][0].xy); VPKFMA(px, P23, Rkk[c][0].zw, px); VPKFMA(py, P23, Rr[pc][0].zw, py);
;                         VPKFMA(px, P45, Rkk[c][1].xy, px); VPKFMA(py, P45, Rr[pc][1].xy, py); VPKFMA(px, P67, Rkk[c][1].zw, px); VPKFMA(py, P67, Rr[pc][1].zw, py);
;                         VADD(x, px.x, px.y); VADD(yp, py.x, py.y);
;                     } else {
;                         VPKMUL(px, P01, Rkk[c][0].xy); VPKFMA(px, P23, Rkk[c][0].zw, px); VPKFMA(px, P45, Rkk[c][1].xy, px); VPKFMA(px, P67, Rkk[c][1].zw, px);
;                         VADD(x, px.x, px.y);
;                     }
;                     asm volatile("" ::: "memory");
;                     if (s + 1 < 32) LOADREC((s + 1) & 1, s + 1);
;                     asm volatile("" ::: "memory");
;                     VPKMULBL(t01, vv2, Rkm[c][0].xy); VPKMULBL(t23, vv2, Rkm[c][0].zw);
;                     VDPP1(x); if (s >= 1) VDPP1(yp);
;                     VPKMULBL(t45, vv2, Rkm[c][1].xy); VPKMULBL(t67, vv2, Rkm[c][1].zw);
;                     VDPP2(x); if (s >= 1) VDPP2(yp);
;                     VPKFMA(P01, P01, Rw[c][0].xy, t01); VPKFMA(P23, P23, Rw[c][0].zw, t23);
;                     VDPP3(x); if (s >= 1) VDPP3(yp);
;                     VPKFMA(P45, P45, Rw[c][1].xy, t45); VPKFMA(P67, P67, Rw[c][1].zw, t67);
;                     if (s >= 1) { if (s - 1 < 8) YSHIFT(yk0); else if (s - 1 < 16) YSHIFT(yk1); else if (s - 1 < 24) YSHIFT(yk2); else YSHIFT(yk3); }
;                     x = x * si;
;                     f32x2 x2; x2.x = x; asm volatile("" : "+v"(x2));
;                     VPKNFMABL(P01, x2, Rka[c][0].xy, P01); VPKNFMABL(P23, x2, Rka[c][0].zw, P23); VPKNFMABL(P45, x2, Rka[c][1].xy, P45); VPKNFMABL(P67, x2, Rka[c][1].zw, P67);
;                 }
	ds_read_b128 v[64:67], v35 offset:8432
	ds_read_b128 v[76:79], v35 offset:34544
	ds_read_b32 v94, v36 offset:3968
	ds_read_b32 v95, v38 offset:3968
	ds_read_b128 v[68:71], v35 offset:17136
	ds_read_b128 v[72:75], v35 offset:25840
	ds_read_b128 v[84:87], v35 offset:43248
	v_pk_mul_f32 v[8:9], v[0:1], v[48:49] op_sel_hi:[1,0]
	v_pk_mul_f32 v[10:11], v[0:1], v[88:89] op_sel_hi:[1,0]
	v_pk_fma_f32 v[8:9], v[2:3], v[48:49], v[8:9] op_sel:[0,1,0] op_sel_hi:[1,1,1]
	v_pk_fma_f32 v[10:11], v[2:3], v[88:89], v[10:11] op_sel:[0,1,0] op_sel_hi:[1,1,1]
	v_pk_fma_f32 v[8:9], v[4:5], v[50:51], v[8:9] op_sel_hi:[1,0,1]
	v_pk_fma_f32 v[10:11], v[4:5], v[90:91], v[10:11] op_sel_hi:[1,0,1]
	v_pk_fma_f32 v[8:9], v[6:7], v[50:51], v[8:9] op_sel:[0,1,0] op_sel_hi:[1,1,1]
	v_pk_fma_f32 v[10:11], v[6:7], v[90:91], v[10:11] op_sel:[0,1,0] op_sel_hi:[1,1,1]
	v_readlane_b32 s10, v34, 30
	v_pk_mul_f32 v[16:17], v[92:93], v[60:61] op_sel_hi:[1,0]
	v_pk_mul_f32 v[18:19], v[92:93], v[60:61] op_sel:[0,1] op_sel_hi:[1,1]
	v_add_f32_dpp v8, v9, v8 quad_perm:[1,0,3,2] row_mask:0xf bank_mask:0xf bound_ctrl:1
	v_add_f32_dpp v10, v11, v10 quad_perm:[1,0,3,2] row_mask:0xf bank_mask:0xf bound_ctrl:1
	v_pk_mul_f32 v[20:21], v[92:93], v[62:63] op_sel_hi:[1,0]
	v_pk_mul_f32 v[22:23], v[92:93], v[62:63] op_sel:[0,1] op_sel_hi:[1,1]
	v_add_f32_dpp v8, v8, v8 quad_perm:[2,3,0,1] row_mask:0xf bank_mask:0xf bound_ctrl:1
	v_add_f32_dpp v10, v10, v10 quad_perm:[2,3,0,1] row_mask:0xf bank_mask:0xf bound_ctrl:1
	v_pk_fma_f32 v[0:1], v[0:1], v[52:53], v[16:17] op_sel_hi:[1,0,1]
	v_pk_fma_f32 v[2:3], v[2:3], v[52:53], v[18:19] op_sel:[0,1,0] op_sel_hi:[1,1,1]
	v_add_f32_dpp v8, v8, v8 row_ror:4 row_mask:0xf bank_mask:0xf bound_ctrl:1
	v_add_f32_dpp v10, v10, v10 row_ror:4 row_mask:0xf bank_mask:0xf bound_ctrl:1
	v_pk_fma_f32 v[4:5], v[4:5], v[54:55], v[20:21] op_sel_hi:[1,0,1]
	v_add_f32_dpp v8, v8, v8 row_ror:8 row_mask:0xf bank_mask:0xf bound_ctrl:1
	v_mul_f32_e32 v8, s10, v8
	v_add_f32_dpp v103, v10, v10 row_ror:8 row_mask:0xf bank_mask:0x2 bound_ctrl:1
	v_pk_fma_f32 v[6:7], v[6:7], v[54:55], v[22:23] op_sel:[0,1,0] op_sel_hi:[1,1,1]
	v_mov_b32_dpp v9, v8 quad_perm:[1,0,3,2] row_mask:0xf bank_mask:0xf
	v_pk_fma_f32 v[0:1], v[8:9], v[56:57], v[0:1] op_sel_hi:[1,0,1] neg_lo:[1,0,0] neg_hi:[1,0,0]
	v_pk_fma_f32 v[2:3], v[8:9], v[56:57], v[2:3] op_sel:[0,1,0] op_sel_hi:[1,1,1] neg_lo:[1,0,0] neg_hi:[1,0,0]
	v_pk_fma_f32 v[4:5], v[8:9], v[58:59], v[4:5] op_sel_hi:[1,0,1] neg_lo:[1,0,0] neg_hi:[1,0,0]
	v_pk_fma_f32 v[6:7], v[8:9], v[58:59], v[6:7] op_sel:[0,1,0] op_sel_hi:[1,1,1] neg_lo:[1,0,0] neg_hi:[1,0,0]
	s_waitcnt lgkmcnt(0)
	v_pk_mul_f32 v[8:9], v[0:1], v[64:65] op_sel_hi:[1,0]
	v_pk_mul_f32 v[10:11], v[0:1], v[80:81] op_sel_hi:[1,0]
	v_pk_fma_f32 v[8:9], v[2:3], v[64:65], v[8:9] op_sel:[0,1,0] op_sel_hi:[1,1,1]
	v_pk_fma_f32 v[10:11], v[2:3], v[80:81], v[10:11] op_sel:[0,1,0] op_sel_hi:[1,1,1]
	v_pk_fma_f32 v[8:9], v[4:5], v[66:67], v[8:9] op_sel_hi:[1,0,1]
	v_pk_fma_f32 v[10:11], v[4:5], v[82:83], v[10:11] op_sel_hi:[1,0,1]
	v_pk_fma_f32 v[8:9], v[6:7], v[66:67], v[8:9] op_sel:[0,1,0] op_sel_hi:[1,1,1]
	v_pk_fma_f32 v[10:11], v[6:7], v[82:83], v[10:11] op_sel:[0,1,0] op_sel_hi:[1,1,1]
	v_readlane_b32 s10, v34, 31
	v_pk_mul_f32 v[16:17], v[94:95], v[76:77] op_sel_hi:[1,0]
	v_pk_mul_f32 v[18:19], v[94:95], v[76:77] op_sel:[0,1] op_sel_hi:[1,1]
	v_add_f32_dpp v8, v9, v8 quad_perm:[1,0,3,2] row_mask:0xf bank_mask:0xf bound_ctrl:1
	v_add_f32_dpp v10, v11, v10 quad_perm:[1,0,3,2] row_mask:0xf bank_mask:0xf bound_ctrl:1
	v_pk_mul_f32 v[20:21], v[94:95], v[78:79] op_sel_hi:[1,0]
	v_pk_mul_f32 v[22:23], v[94:95], v[78:79] op_sel:[0,1] op_sel_hi:[1,1]
	v_add_f32_dpp v8, v8, v8 quad_perm:[2,3,0,1] row_mask:0xf bank_mask:0xf bound_ctrl:1
	v_add_f32_dpp v10, v10, v10 quad_perm:[2,3,0,1] row_mask:0xf bank_mask:0xf bound_ctrl:1
	v_pk_fma_f32 v[0:1], v[0:1], v[68:69], v[16:17] op_sel_hi:[1,0,1]
	v_pk_fma_f32 v[2:3], v[2:3], v[68:69], v[18:19] op_sel:[0,1,0] op_sel_hi:[1,1,1]
	v_add_f32_dpp v8, v8, v8 row_ror:4 row_mask:0xf bank_mask:0xf bound_ctrl:1
	v_add_f32_dpp v10, v10, v10 row_ror:4 row_mask:0xf bank_mask:0xf bound_ctrl:1
	v_pk_fma_f32 v[4:5], v[4:5], v[70:71], v[20:21] op_sel_hi:[1,0,1]
	v_add_f32_dpp v8, v8, v8 row_ror:8 row_mask:0xf bank_mask:0xf bound_ctrl:1
	v_mul_f32_e32 v8, s10, v8
	v_add_f32_dpp v103, v10, v10 row_ror:8 row_mask:0xf bank_mask:0x4 bound_ctrl:1
	v_pk_fma_f32 v[6:7], v[6:7], v[70:71], v[22:23] op_sel:[0,1,0] op_sel_hi:[1,1,1]
	v_mov_b32_dpp v9, v8 quad_perm:[1,0,3,2] row_mask:0xf bank_mask:0xf
	v_pk_fma_f32 v[0:1], v[8:9], v[72:73], v[0:1] op_sel_hi:[1,0,1] neg_lo:[1,0,0] neg_hi:[1,0,0]
	v_pk_fma_f32 v[2:3], v[8:9], v[72:73], v[2:3] op_sel:[0,1,0] op_sel_hi:[1,1,1] neg_lo:[1,0,0] neg_hi:[1,0,0]
	v_pk_fma_f32 v[4:5], v[8:9], v[74:75], v[4:5] op_sel_hi:[1,0,1] neg_lo:[1,0,0] neg_hi:[1,0,0]
	v_pk_fma_f32 v[6:7], v[8:9], v[74:75], v[6:7] op_sel:[0,1,0] op_sel_hi:[1,1,1] neg_lo:[1,0,0] neg_hi:[1,0,0]
	v_pk_mul_f32 v[10:11], v[0:1], v[84:85] op_sel_hi:[1,0]
	v_pk_fma_f32 v[10:11], v[2:3], v[84:85], v[10:11] op_sel:[0,1,0] op_sel_hi:[1,1,1]
	v_pk_fma_f32 v[10:11], v[4:5], v[86:87], v[10:11] op_sel_hi:[1,0,1]
	v_pk_fma_f32 v[10:11], v[6:7], v[86:87], v[10:11] op_sel:[0,1,0] op_sel_hi:[1,1,1]
	s_nop 1
	v_add_f32_dpp v10, v11, v10 quad_perm:[1,0,3,2] row_mask:0xf bank_mask:0xf bound_ctrl:1
	s_nop 1
	v_add_f32_dpp v10, v10, v10 quad_perm:[2,3,0,1] row_mask:0xf bank_mask:0xf bound_ctrl:1
	s_nop 1
	v_add_f32_dpp v10, v10, v10 row_ror:4 row_mask:0xf bank_mask:0xf bound_ctrl:1
	s_nop 1
	v_add_f32_dpp v103, v10, v10 row_ror:8 row_mask:0xf bank_mask:0x8 bound_ctrl:1
	ds_write_b32 v37, v96 offset:0
	ds_write_b32 v37, v97 offset:512
	ds_write_b32 v37, v98 offset:1024
	ds_write_b32 v37, v99 offset:1536
	ds_write_b32 v37, v100 offset:2048
	ds_write_b32 v37, v101 offset:2560
	ds_write_b32 v37, v102 offset:3072
	ds_write_b32 v37, v103 offset:3584
